# GEMM K-loops: s_setprio toggles around the MFMA blocks removed (both wave halves at equal priority); on top of the attention-loop trims
# baseline (speedup 1.0000x reference)
.LBB0_159:
	ds_read_b128 v[128:131], v149
	ds_read_b128 v[132:135], v149 offset:1024
	ds_read_b128 v[168:171], v149 offset:2048
	ds_read_b128 v[176:179], v149 offset:3072
	ds_read_b128 v[180:183], v174
	ds_read_b128 v[184:187], v174 offset:1024
	ds_read_b128 v[188:191], v174 offset:2048
	ds_read_b128 v[192:195], v174 offset:3072
	s_add_u32 s42, s40, 0xfff80080
	s_addc_u32 s43, s41, -1
	s_cmp_eq_u32 s49, 28
	s_cselect_b32 s45, s0, s43
	s_cselect_b32 s44, s5, s42
	s_cselect_b32 s43, s29, s48
	s_cselect_b32 s42, s31, s33
	v_lshl_add_u64 v[172:173], s[40:41], 0, v[154:155]
	s_add_i32 m0, s39, 0xc000
	ds_read_b128 v[196:199], v175
	ds_read_b128 v[200:203], v175 offset:1024
	ds_read_b128 v[204:207], v175 offset:2048
	ds_read_b128 v[208:211], v175 offset:3072
	ds_read_b128 v[214:217], v175 offset:4096
	ds_read_b128 v[218:221], v175 offset:5120
	ds_read_b128 v[222:225], v175 offset:6144
	ds_read_b128 v[226:229], v175 offset:7168
	global_load_lds_dwordx4 v[172:173], off
	v_lshl_add_u64 v[172:173], s[40:41], 0, v[156:157]
	s_add_i32 m0, s39, 0xe000
	s_nop 0
	global_load_lds_dwordx4 v[172:173], off
	s_waitcnt vmcnt(8)
	s_waitcnt lgkmcnt(0)
	s_barrier
	s_waitcnt lgkmcnt(0)
	v_mfma_f32_16x16x32_bf16 v[124:127], v[128:131], v[196:199], v[124:127]
	v_mfma_f32_16x16x32_bf16 v[120:123], v[168:171], v[196:199], v[120:123]
	v_mfma_f32_16x16x32_bf16 v[108:111], v[128:131], v[204:207], v[108:111]
	v_mfma_f32_16x16x32_bf16 v[104:107], v[168:171], v[204:207], v[104:107]
	v_mfma_f32_16x16x32_bf16 v[92:95], v[128:131], v[214:217], v[92:95]
	v_mfma_f32_16x16x32_bf16 v[88:91], v[168:171], v[214:217], v[88:91]
	v_mfma_f32_16x16x32_bf16 v[76:79], v[128:131], v[222:225], v[76:79]
	v_mfma_f32_16x16x32_bf16 v[72:75], v[168:171], v[222:225], v[72:75]
	v_mfma_f32_16x16x32_bf16 v[124:127], v[132:135], v[200:203], v[124:127]
	v_mfma_f32_16x16x32_bf16 v[120:123], v[176:179], v[200:203], v[120:123]
	v_mfma_f32_16x16x32_bf16 v[108:111], v[132:135], v[208:211], v[108:111]
	v_mfma_f32_16x16x32_bf16 v[104:107], v[176:179], v[208:211], v[104:107]
	v_mfma_f32_16x16x32_bf16 v[92:95], v[132:135], v[218:221], v[92:95]
	v_mfma_f32_16x16x32_bf16 v[88:91], v[176:179], v[218:221], v[88:91]
	v_mfma_f32_16x16x32_bf16 v[76:79], v[132:135], v[226:229], v[76:79]
	v_mfma_f32_16x16x32_bf16 v[72:75], v[176:179], v[226:229], v[72:75]
	v_mfma_f32_16x16x32_bf16 v[116:119], v[180:183], v[196:199], v[116:119]
	v_mfma_f32_16x16x32_bf16 v[112:115], v[188:191], v[196:199], v[112:115]
	v_mfma_f32_16x16x32_bf16 v[100:103], v[180:183], v[204:207], v[100:103]
	v_mfma_f32_16x16x32_bf16 v[96:99], v[188:191], v[204:207], v[96:99]
	v_mfma_f32_16x16x32_bf16 v[84:87], v[180:183], v[214:217], v[84:87]
	v_mfma_f32_16x16x32_bf16 v[80:83], v[188:191], v[214:217], v[80:83]
	v_mfma_f32_16x16x32_bf16 v[68:71], v[180:183], v[222:225], v[68:71]
	v_mfma_f32_16x16x32_bf16 v[64:67], v[188:191], v[222:225], v[64:67]
	v_mfma_f32_16x16x32_bf16 v[116:119], v[184:187], v[200:203], v[116:119]
	v_mfma_f32_16x16x32_bf16 v[112:115], v[192:195], v[200:203], v[112:115]
	v_mfma_f32_16x16x32_bf16 v[100:103], v[184:187], v[208:211], v[100:103]
	v_mfma_f32_16x16x32_bf16 v[96:99], v[192:195], v[208:211], v[96:99]
	v_mfma_f32_16x16x32_bf16 v[84:87], v[184:187], v[218:221], v[84:87]
	v_mfma_f32_16x16x32_bf16 v[80:83], v[192:195], v[218:221], v[80:83]
	v_mfma_f32_16x16x32_bf16 v[68:71], v[184:187], v[226:229], v[68:71]
	v_mfma_f32_16x16x32_bf16 v[64:67], v[192:195], v[226:229], v[64:67]
	s_barrier
	s_add_i32 s52, s23, s66
	v_lshl_add_u64 v[172:173], s[42:43], 0, v[138:139]
	s_mov_b32 m0, s52
	ds_read_b128 v[196:199], v175 offset:16384
	ds_read_b128 v[200:203], v175 offset:17408
	ds_read_b128 v[204:207], v175 offset:18432
	ds_read_b128 v[208:211], v175 offset:19456
	ds_read_b128 v[214:217], v175 offset:20480
	ds_read_b128 v[218:221], v175 offset:21504
	ds_read_b128 v[222:225], v175 offset:22528
	ds_read_b128 v[226:229], v175 offset:23552
	global_load_lds_dwordx4 v[172:173], off
	s_add_i32 m0, s52, 0x2000
	s_add_u32 s52, s42, 0x80000
	v_lshl_add_u64 v[230:231], s[42:43], 0, v[142:143]
	s_addc_u32 s53, s43, 0
	s_add_i32 s54, s93, s66
	global_load_lds_dwordx4 v[230:231], off
	v_lshl_add_u64 v[232:233], s[52:53], 0, v[138:139]
	s_mov_b32 m0, s54
	v_lshl_add_u64 v[234:235], s[44:45], 0, v[140:141]
	global_load_lds_dwordx4 v[232:233], off
	v_lshl_add_u64 v[232:233], s[52:53], 0, v[142:143]
	s_add_i32 m0, s54, 0x2000
	s_nop 0
	global_load_lds_dwordx4 v[232:233], off
	v_lshl_add_u64 v[232:233], s[44:45], 0, v[136:137]
	s_mov_b32 m0, s39
	s_nop 0
	global_load_lds_dwordx4 v[232:233], off
	s_mov_b32 m0, s67
	s_nop 0
	global_load_lds_dwordx4 v[234:235], off
	s_waitcnt vmcnt(8)
	s_waitcnt lgkmcnt(0)
	s_barrier
	s_waitcnt lgkmcnt(0)
	v_mfma_f32_16x16x32_bf16 v[60:63], v[128:131], v[196:199], v[60:63]
	v_mfma_f32_16x16x32_bf16 v[56:59], v[168:171], v[196:199], v[56:59]
	v_mfma_f32_16x16x32_bf16 v[44:47], v[128:131], v[204:207], v[44:47]
	v_mfma_f32_16x16x32_bf16 v[40:43], v[168:171], v[204:207], v[40:43]
	v_mfma_f32_16x16x32_bf16 v[28:31], v[128:131], v[214:217], v[28:31]
	v_mfma_f32_16x16x32_bf16 v[24:27], v[168:171], v[214:217], v[24:27]
	v_mfma_f32_16x16x32_bf16 v[12:15], v[128:131], v[222:225], v[12:15]
	v_mfma_f32_16x16x32_bf16 v[8:11], v[168:171], v[222:225], v[8:11]
	v_mfma_f32_16x16x32_bf16 v[60:63], v[132:135], v[200:203], v[60:63]
	v_mfma_f32_16x16x32_bf16 v[56:59], v[176:179], v[200:203], v[56:59]
	v_mfma_f32_16x16x32_bf16 v[44:47], v[132:135], v[208:211], v[44:47]
	v_mfma_f32_16x16x32_bf16 v[40:43], v[176:179], v[208:211], v[40:43]
	v_mfma_f32_16x16x32_bf16 v[28:31], v[132:135], v[218:221], v[28:31]
	v_mfma_f32_16x16x32_bf16 v[24:27], v[176:179], v[218:221], v[24:27]
	v_mfma_f32_16x16x32_bf16 v[12:15], v[132:135], v[226:229], v[12:15]
	v_mfma_f32_16x16x32_bf16 v[8:11], v[176:179], v[226:229], v[8:11]
	v_mfma_f32_16x16x32_bf16 v[52:55], v[180:183], v[196:199], v[52:55]
	v_mfma_f32_16x16x32_bf16 v[48:51], v[188:191], v[196:199], v[48:51]
	v_mfma_f32_16x16x32_bf16 v[36:39], v[180:183], v[204:207], v[36:39]
	v_mfma_f32_16x16x32_bf16 v[32:35], v[188:191], v[204:207], v[32:35]
	v_mfma_f32_16x16x32_bf16 v[20:23], v[180:183], v[214:217], v[20:23]
	v_mfma_f32_16x16x32_bf16 v[16:19], v[188:191], v[214:217], v[16:19]
	v_mfma_f32_16x16x32_bf16 v[4:7], v[180:183], v[222:225], v[4:7]
	v_mfma_f32_16x16x32_bf16 v[0:3], v[188:191], v[222:225], v[0:3]
	v_mfma_f32_16x16x32_bf16 v[52:55], v[184:187], v[200:203], v[52:55]
	v_mfma_f32_16x16x32_bf16 v[48:51], v[192:195], v[200:203], v[48:51]
	v_mfma_f32_16x16x32_bf16 v[36:39], v[184:187], v[208:211], v[36:39]
	v_mfma_f32_16x16x32_bf16 v[32:35], v[192:195], v[208:211], v[32:35]
	v_mfma_f32_16x16x32_bf16 v[20:23], v[184:187], v[218:221], v[20:23]
	v_mfma_f32_16x16x32_bf16 v[16:19], v[192:195], v[218:221], v[16:19]
	v_mfma_f32_16x16x32_bf16 v[4:7], v[184:187], v[226:229], v[4:7]
	v_mfma_f32_16x16x32_bf16 v[0:3], v[192:195], v[226:229], v[0:3]
	s_barrier
	s_add_i32 s52, 0, 0x18000
	v_add_u32_e32 v144, s52, v147
	s_add_i32 s53, 0, 0x1c000
	ds_read_b128 v[128:131], v144
	ds_read_b128 v[132:135], v144 offset:1024
	ds_read_b128 v[168:171], v144 offset:2048
	ds_read_b128 v[176:179], v144 offset:3072
	v_add_u32_e32 v144, s53, v147
	ds_read_b128 v[180:183], v144
	ds_read_b128 v[184:187], v144 offset:1024
	ds_read_b128 v[188:191], v144 offset:2048
	ds_read_b128 v[192:195], v144 offset:3072
	s_add_u32 s44, s44, 0x80000
	s_addc_u32 s45, s45, 0
	s_mov_b32 m0, s89
	v_lshl_add_u64 v[236:237], s[44:45], 0, v[136:137]
	ds_read_b128 v[196:199], v175 offset:32768
	ds_read_b128 v[200:203], v175 offset:33792
	ds_read_b128 v[204:207], v175 offset:34816
	ds_read_b128 v[208:211], v175 offset:35840
	ds_read_b128 v[214:217], v175 offset:36864
	ds_read_b128 v[218:221], v175 offset:37888
	ds_read_b128 v[222:225], v175 offset:38912
	ds_read_b128 v[226:229], v175 offset:39936
	global_load_lds_dwordx4 v[236:237], off
	v_lshl_add_u64 v[236:237], s[44:45], 0, v[140:141]
	s_mov_b32 m0, s91
	s_nop 0
	global_load_lds_dwordx4 v[236:237], off
	s_waitcnt vmcnt(8)
	s_waitcnt lgkmcnt(0)
	s_barrier
	s_waitcnt lgkmcnt(0)
	v_mfma_f32_16x16x32_bf16 v[124:127], v[128:131], v[196:199], v[124:127]
	v_mfma_f32_16x16x32_bf16 v[120:123], v[168:171], v[196:199], v[120:123]
	v_mfma_f32_16x16x32_bf16 v[108:111], v[128:131], v[204:207], v[108:111]
	v_mfma_f32_16x16x32_bf16 v[104:107], v[168:171], v[204:207], v[104:107]
	v_mfma_f32_16x16x32_bf16 v[92:95], v[128:131], v[214:217], v[92:95]
	v_mfma_f32_16x16x32_bf16 v[88:91], v[168:171], v[214:217], v[88:91]
	v_mfma_f32_16x16x32_bf16 v[76:79], v[128:131], v[222:225], v[76:79]
	v_mfma_f32_16x16x32_bf16 v[72:75], v[168:171], v[222:225], v[72:75]
	v_mfma_f32_16x16x32_bf16 v[124:127], v[132:135], v[200:203], v[124:127]
	v_mfma_f32_16x16x32_bf16 v[120:123], v[176:179], v[200:203], v[120:123]
	v_mfma_f32_16x16x32_bf16 v[108:111], v[132:135], v[208:211], v[108:111]
	v_mfma_f32_16x16x32_bf16 v[104:107], v[176:179], v[208:211], v[104:107]
	v_mfma_f32_16x16x32_bf16 v[92:95], v[132:135], v[218:221], v[92:95]
	v_mfma_f32_16x16x32_bf16 v[88:91], v[176:179], v[218:221], v[88:91]
	v_mfma_f32_16x16x32_bf16 v[76:79], v[132:135], v[226:229], v[76:79]
	v_mfma_f32_16x16x32_bf16 v[72:75], v[176:179], v[226:229], v[72:75]
	v_mfma_f32_16x16x32_bf16 v[116:119], v[180:183], v[196:199], v[116:119]
	v_mfma_f32_16x16x32_bf16 v[112:115], v[188:191], v[196:199], v[112:115]
	v_mfma_f32_16x16x32_bf16 v[100:103], v[180:183], v[204:207], v[100:103]
	v_mfma_f32_16x16x32_bf16 v[96:99], v[188:191], v[204:207], v[96:99]
	v_mfma_f32_16x16x32_bf16 v[84:87], v[180:183], v[214:217], v[84:87]
	v_mfma_f32_16x16x32_bf16 v[80:83], v[188:191], v[214:217], v[80:83]
	v_mfma_f32_16x16x32_bf16 v[68:71], v[180:183], v[222:225], v[68:71]
	v_mfma_f32_16x16x32_bf16 v[64:67], v[188:191], v[222:225], v[64:67]
	v_mfma_f32_16x16x32_bf16 v[116:119], v[184:187], v[200:203], v[116:119]
	v_mfma_f32_16x16x32_bf16 v[112:115], v[192:195], v[200:203], v[112:115]
	v_mfma_f32_16x16x32_bf16 v[100:103], v[184:187], v[208:211], v[100:103]
	v_mfma_f32_16x16x32_bf16 v[96:99], v[192:195], v[208:211], v[96:99]
	v_mfma_f32_16x16x32_bf16 v[84:87], v[184:187], v[218:221], v[84:87]
	v_mfma_f32_16x16x32_bf16 v[80:83], v[192:195], v[218:221], v[80:83]
	v_mfma_f32_16x16x32_bf16 v[68:71], v[184:187], v[226:229], v[68:71]
	v_mfma_f32_16x16x32_bf16 v[64:67], v[192:195], v[226:229], v[64:67]
	s_barrier
	s_add_i32 s44, s52, s66
	v_lshl_add_u64 v[172:173], v[172:173], 0, s[8:9]
	s_mov_b32 m0, s44
	ds_read_b128 v[196:199], v175 offset:49152
	ds_read_b128 v[200:203], v175 offset:50176
	ds_read_b128 v[204:207], v175 offset:51200
	ds_read_b128 v[208:211], v175 offset:52224
	ds_read_b128 v[214:217], v175 offset:53248
	ds_read_b128 v[218:221], v175 offset:54272
	ds_read_b128 v[222:225], v175 offset:55296
	ds_read_b128 v[226:229], v175 offset:56320
	global_load_lds_dwordx4 v[172:173], off
	s_add_i32 m0, s44, 0x2000
	s_add_u32 s42, s42, 0x80080
	v_lshl_add_u64 v[172:173], v[230:231], 0, s[8:9]
	s_addc_u32 s43, s43, 0
	s_add_i32 s44, s53, s66
	global_load_lds_dwordx4 v[172:173], off
	v_lshl_add_u64 v[172:173], s[42:43], 0, v[138:139]
	s_mov_b32 m0, s44
	s_nop 0
	global_load_lds_dwordx4 v[172:173], off
	v_lshl_add_u64 v[172:173], s[42:43], 0, v[142:143]
	s_add_i32 m0, s44, 0x2000
	s_nop 0
	global_load_lds_dwordx4 v[172:173], off
	v_lshl_add_u64 v[172:173], v[232:233], 0, s[8:9]
	s_mov_b32 m0, s46
	s_nop 0
	global_load_lds_dwordx4 v[172:173], off
	v_lshl_add_u64 v[172:173], v[234:235], 0, s[8:9]
	s_mov_b32 m0, s47
	s_nop 0
	global_load_lds_dwordx4 v[172:173], off
	s_waitcnt vmcnt(8)
	s_waitcnt lgkmcnt(0)
	s_barrier
	s_waitcnt lgkmcnt(0)
	v_mfma_f32_16x16x32_bf16 v[60:63], v[128:131], v[196:199], v[60:63]
	v_mfma_f32_16x16x32_bf16 v[56:59], v[168:171], v[196:199], v[56:59]
	v_mfma_f32_16x16x32_bf16 v[44:47], v[128:131], v[204:207], v[44:47]
	v_mfma_f32_16x16x32_bf16 v[40:43], v[168:171], v[204:207], v[40:43]
	v_mfma_f32_16x16x32_bf16 v[28:31], v[128:131], v[214:217], v[28:31]
	v_mfma_f32_16x16x32_bf16 v[24:27], v[168:171], v[214:217], v[24:27]
	v_mfma_f32_16x16x32_bf16 v[12:15], v[128:131], v[222:225], v[12:15]
	v_mfma_f32_16x16x32_bf16 v[8:11], v[168:171], v[222:225], v[8:11]
	v_mfma_f32_16x16x32_bf16 v[60:63], v[132:135], v[200:203], v[60:63]
	v_mfma_f32_16x16x32_bf16 v[56:59], v[176:179], v[200:203], v[56:59]
	v_mfma_f32_16x16x32_bf16 v[44:47], v[132:135], v[208:211], v[44:47]
	v_mfma_f32_16x16x32_bf16 v[40:43], v[176:179], v[208:211], v[40:43]
	v_mfma_f32_16x16x32_bf16 v[28:31], v[132:135], v[218:221], v[28:31]
	v_mfma_f32_16x16x32_bf16 v[24:27], v[176:179], v[218:221], v[24:27]
	v_mfma_f32_16x16x32_bf16 v[12:15], v[132:135], v[226:229], v[12:15]
	v_mfma_f32_16x16x32_bf16 v[8:11], v[176:179], v[226:229], v[8:11]
	v_mfma_f32_16x16x32_bf16 v[52:55], v[180:183], v[196:199], v[52:55]
	v_mfma_f32_16x16x32_bf16 v[48:51], v[188:191], v[196:199], v[48:51]
	v_mfma_f32_16x16x32_bf16 v[36:39], v[180:183], v[204:207], v[36:39]
	v_mfma_f32_16x16x32_bf16 v[32:35], v[188:191], v[204:207], v[32:35]
	v_mfma_f32_16x16x32_bf16 v[20:23], v[180:183], v[214:217], v[20:23]
	v_mfma_f32_16x16x32_bf16 v[16:19], v[188:191], v[214:217], v[16:19]
	v_mfma_f32_16x16x32_bf16 v[4:7], v[180:183], v[222:225], v[4:7]
	v_mfma_f32_16x16x32_bf16 v[0:3], v[188:191], v[222:225], v[0:3]
	v_mfma_f32_16x16x32_bf16 v[52:55], v[184:187], v[200:203], v[52:55]
	v_mfma_f32_16x16x32_bf16 v[48:51], v[192:195], v[200:203], v[48:51]
	v_mfma_f32_16x16x32_bf16 v[36:39], v[184:187], v[208:211], v[36:39]
	v_mfma_f32_16x16x32_bf16 v[32:35], v[192:195], v[208:211], v[32:35]
	v_mfma_f32_16x16x32_bf16 v[20:23], v[184:187], v[218:221], v[20:23]
	v_mfma_f32_16x16x32_bf16 v[16:19], v[192:195], v[218:221], v[16:19]
	v_mfma_f32_16x16x32_bf16 v[4:7], v[184:187], v[226:229], v[4:7]
	v_mfma_f32_16x16x32_bf16 v[0:3], v[192:195], v[226:229], v[0:3]
	s_barrier
	s_add_i32 s49, s49, 2
	s_add_u32 s40, s40, 0x100
	s_addc_u32 s41, s41, 0
	s_add_u32 s33, s33, 0x100
	s_addc_u32 s48, s48, 0
	s_cmp_gt_u32 s49, 29
	s_cbranch_scc0 .LBB0_159
	s_and_b64 vcc, exec, s[10:11]
	s_cbranch_vccz .LBB0_162
	s_barrier

.LBB0_374:
	ds_read_b128 v[140:143], v147
	ds_read_b128 v[150:153], v147 offset:1024
	ds_read_b128 v[154:157], v147 offset:2048
	ds_read_b128 v[158:161], v147 offset:3072
	ds_read_b128 v[162:165], v148
	ds_read_b128 v[166:169], v148 offset:1024
	ds_read_b128 v[170:173], v148 offset:2048
	ds_read_b128 v[174:177], v148 offset:3072
	s_add_u32 s22, s20, 0xfff80080
	s_addc_u32 s23, s21, -1
	s_cmp_eq_u32 s45, 28
	s_cselect_b32 s25, s11, s23
	s_cselect_b32 s24, s41, s22
	s_cselect_b32 s23, s9, s44
	s_cselect_b32 s22, s42, s43
	v_lshl_add_u64 v[210:211], s[20:21], 0, v[132:133]
	s_add_i32 m0, s19, 0xc000
	ds_read_b128 v[178:181], v149
	ds_read_b128 v[182:185], v149 offset:1024
	ds_read_b128 v[186:189], v149 offset:2048
	ds_read_b128 v[190:193], v149 offset:3072
	ds_read_b128 v[194:197], v149 offset:4096
	ds_read_b128 v[198:201], v149 offset:5120
	ds_read_b128 v[202:205], v149 offset:6144
	ds_read_b128 v[206:209], v149 offset:7168
	global_load_lds_dwordx4 v[210:211], off
	v_lshl_add_u64 v[210:211], s[20:21], 0, v[134:135]
	s_add_i32 m0, s19, 0xe000
	s_nop 0
	global_load_lds_dwordx4 v[210:211], off
	s_waitcnt vmcnt(8)
	s_waitcnt lgkmcnt(0)
	s_barrier
	s_waitcnt lgkmcnt(0)
	v_mfma_f32_16x16x32_bf16 v[124:127], v[140:143], v[178:181], v[124:127]
	v_mfma_f32_16x16x32_bf16 v[120:123], v[154:157], v[178:181], v[120:123]
	v_mfma_f32_16x16x32_bf16 v[112:115], v[140:143], v[186:189], v[112:115]
	v_mfma_f32_16x16x32_bf16 v[108:111], v[154:157], v[186:189], v[108:111]
	v_mfma_f32_16x16x32_bf16 v[96:99], v[140:143], v[194:197], v[96:99]
	v_mfma_f32_16x16x32_bf16 v[92:95], v[154:157], v[194:197], v[92:95]
	v_mfma_f32_16x16x32_bf16 v[80:83], v[140:143], v[202:205], v[80:83]
	v_mfma_f32_16x16x32_bf16 v[76:79], v[154:157], v[202:205], v[76:79]
	v_mfma_f32_16x16x32_bf16 v[124:127], v[150:153], v[182:185], v[124:127]
	v_mfma_f32_16x16x32_bf16 v[120:123], v[158:161], v[182:185], v[120:123]
	v_mfma_f32_16x16x32_bf16 v[112:115], v[150:153], v[190:193], v[112:115]
	v_mfma_f32_16x16x32_bf16 v[108:111], v[158:161], v[190:193], v[108:111]
	v_mfma_f32_16x16x32_bf16 v[96:99], v[150:153], v[198:201], v[96:99]
	v_mfma_f32_16x16x32_bf16 v[92:95], v[158:161], v[198:201], v[92:95]
	v_mfma_f32_16x16x32_bf16 v[80:83], v[150:153], v[206:209], v[80:83]
	v_mfma_f32_16x16x32_bf16 v[76:79], v[158:161], v[206:209], v[76:79]
	v_mfma_f32_16x16x32_bf16 v[116:119], v[162:165], v[178:181], v[116:119]
	v_mfma_f32_16x16x32_bf16 v[104:107], v[170:173], v[178:181], v[104:107]
	v_mfma_f32_16x16x32_bf16 v[100:103], v[162:165], v[186:189], v[100:103]
	v_mfma_f32_16x16x32_bf16 v[88:91], v[170:173], v[186:189], v[88:91]
	v_mfma_f32_16x16x32_bf16 v[84:87], v[162:165], v[194:197], v[84:87]
	v_mfma_f32_16x16x32_bf16 v[72:75], v[170:173], v[194:197], v[72:75]
	v_mfma_f32_16x16x32_bf16 v[68:71], v[162:165], v[202:205], v[68:71]
	v_mfma_f32_16x16x32_bf16 v[64:67], v[170:173], v[202:205], v[64:67]
	v_mfma_f32_16x16x32_bf16 v[116:119], v[166:169], v[182:185], v[116:119]
	v_mfma_f32_16x16x32_bf16 v[104:107], v[174:177], v[182:185], v[104:107]
	v_mfma_f32_16x16x32_bf16 v[100:103], v[166:169], v[190:193], v[100:103]
	v_mfma_f32_16x16x32_bf16 v[88:91], v[174:177], v[190:193], v[88:91]
	v_mfma_f32_16x16x32_bf16 v[84:87], v[166:169], v[198:201], v[84:87]
	v_mfma_f32_16x16x32_bf16 v[72:75], v[174:177], v[198:201], v[72:75]
	v_mfma_f32_16x16x32_bf16 v[68:71], v[166:169], v[206:209], v[68:71]
	v_mfma_f32_16x16x32_bf16 v[64:67], v[174:177], v[206:209], v[64:67]
	s_barrier
	s_add_i32 s46, s38, s28
	v_lshl_add_u64 v[210:211], s[22:23], 0, v[128:129]
	s_mov_b32 m0, s46
	ds_read_b128 v[178:181], v149 offset:16384
	ds_read_b128 v[182:185], v149 offset:17408
	ds_read_b128 v[186:189], v149 offset:18432
	ds_read_b128 v[190:193], v149 offset:19456
	ds_read_b128 v[194:197], v149 offset:20480
	ds_read_b128 v[198:201], v149 offset:21504
	ds_read_b128 v[202:205], v149 offset:22528
	ds_read_b128 v[206:209], v149 offset:23552
	global_load_lds_dwordx4 v[210:211], off
	s_add_i32 m0, s46, 0x2000
	s_add_u32 s46, s22, 0x80000
	v_lshl_add_u64 v[214:215], s[22:23], 0, v[130:131]
	s_addc_u32 s47, s23, 0
	s_add_i32 s48, s39, s28
	global_load_lds_dwordx4 v[214:215], off
	v_lshl_add_u64 v[216:217], s[46:47], 0, v[128:129]
	s_mov_b32 m0, s48
	v_lshl_add_u64 v[218:219], s[24:25], 0, v[130:131]
	global_load_lds_dwordx4 v[216:217], off
	v_lshl_add_u64 v[216:217], s[46:47], 0, v[130:131]
	s_add_i32 m0, s48, 0x2000
	s_nop 0
	global_load_lds_dwordx4 v[216:217], off
	v_lshl_add_u64 v[216:217], s[24:25], 0, v[128:129]
	s_mov_b32 m0, s19
	s_nop 0
	global_load_lds_dwordx4 v[216:217], off
	s_mov_b32 m0, s29
	s_nop 0
	global_load_lds_dwordx4 v[218:219], off
	s_waitcnt vmcnt(8)
	s_waitcnt lgkmcnt(0)
	s_barrier
	s_waitcnt lgkmcnt(0)
	v_mfma_f32_16x16x32_bf16 v[60:63], v[140:143], v[178:181], v[60:63]
	v_mfma_f32_16x16x32_bf16 v[56:59], v[154:157], v[178:181], v[56:59]
	v_mfma_f32_16x16x32_bf16 v[48:51], v[140:143], v[186:189], v[48:51]
	v_mfma_f32_16x16x32_bf16 v[44:47], v[154:157], v[186:189], v[44:47]
	v_mfma_f32_16x16x32_bf16 v[32:35], v[140:143], v[194:197], v[32:35]
	v_mfma_f32_16x16x32_bf16 v[28:31], v[154:157], v[194:197], v[28:31]
	v_mfma_f32_16x16x32_bf16 v[16:19], v[140:143], v[202:205], v[16:19]
	v_mfma_f32_16x16x32_bf16 v[12:15], v[154:157], v[202:205], v[12:15]
	v_mfma_f32_16x16x32_bf16 v[60:63], v[150:153], v[182:185], v[60:63]
	v_mfma_f32_16x16x32_bf16 v[56:59], v[158:161], v[182:185], v[56:59]
	v_mfma_f32_16x16x32_bf16 v[48:51], v[150:153], v[190:193], v[48:51]
	v_mfma_f32_16x16x32_bf16 v[44:47], v[158:161], v[190:193], v[44:47]
	v_mfma_f32_16x16x32_bf16 v[32:35], v[150:153], v[198:201], v[32:35]
	v_mfma_f32_16x16x32_bf16 v[28:31], v[158:161], v[198:201], v[28:31]
	v_mfma_f32_16x16x32_bf16 v[16:19], v[150:153], v[206:209], v[16:19]
	v_mfma_f32_16x16x32_bf16 v[12:15], v[158:161], v[206:209], v[12:15]
	v_mfma_f32_16x16x32_bf16 v[52:55], v[162:165], v[178:181], v[52:55]
	v_mfma_f32_16x16x32_bf16 v[40:43], v[170:173], v[178:181], v[40:43]
	v_mfma_f32_16x16x32_bf16 v[36:39], v[162:165], v[186:189], v[36:39]
	v_mfma_f32_16x16x32_bf16 v[24:27], v[170:173], v[186:189], v[24:27]
	v_mfma_f32_16x16x32_bf16 v[20:23], v[162:165], v[194:197], v[20:23]
	v_mfma_f32_16x16x32_bf16 v[8:11], v[170:173], v[194:197], v[8:11]
	v_mfma_f32_16x16x32_bf16 v[4:7], v[162:165], v[202:205], v[4:7]
	v_mfma_f32_16x16x32_bf16 v[0:3], v[170:173], v[202:205], v[0:3]
	v_mfma_f32_16x16x32_bf16 v[52:55], v[166:169], v[182:185], v[52:55]
	v_mfma_f32_16x16x32_bf16 v[40:43], v[174:177], v[182:185], v[40:43]
	v_mfma_f32_16x16x32_bf16 v[36:39], v[166:169], v[190:193], v[36:39]
	v_mfma_f32_16x16x32_bf16 v[24:27], v[174:177], v[190:193], v[24:27]
	v_mfma_f32_16x16x32_bf16 v[20:23], v[166:169], v[198:201], v[20:23]
	v_mfma_f32_16x16x32_bf16 v[8:11], v[174:177], v[198:201], v[8:11]
	v_mfma_f32_16x16x32_bf16 v[4:7], v[166:169], v[206:209], v[4:7]
	v_mfma_f32_16x16x32_bf16 v[0:3], v[174:177], v[206:209], v[0:3]
	s_barrier
	s_add_i32 s46, 0, 0x18000
	s_add_i32 s47, 0, 0x1c000
	v_add_u32_e32 v158, s46, v145
	v_add_u32_e32 v174, s47, v145
	ds_read_b128 v[140:143], v158
	ds_read_b128 v[150:153], v158 offset:1024
	ds_read_b128 v[154:157], v158 offset:2048
	ds_read_b128 v[158:161], v158 offset:3072
	ds_read_b128 v[162:165], v174
	ds_read_b128 v[166:169], v174 offset:1024
	ds_read_b128 v[170:173], v174 offset:2048
	ds_read_b128 v[174:177], v174 offset:3072
	s_add_u32 s24, s24, 0x80000
	s_addc_u32 s25, s25, 0
	s_mov_b32 m0, s30
	v_lshl_add_u64 v[220:221], s[24:25], 0, v[128:129]
	ds_read_b128 v[178:181], v149 offset:32768
	ds_read_b128 v[182:185], v149 offset:33792
	ds_read_b128 v[186:189], v149 offset:34816
	ds_read_b128 v[190:193], v149 offset:35840
	ds_read_b128 v[194:197], v149 offset:36864
	ds_read_b128 v[198:201], v149 offset:37888
	ds_read_b128 v[202:205], v149 offset:38912
	ds_read_b128 v[206:209], v149 offset:39936
	global_load_lds_dwordx4 v[220:221], off
	v_lshl_add_u64 v[220:221], s[24:25], 0, v[130:131]
	s_mov_b32 m0, s31
	s_nop 0
	global_load_lds_dwordx4 v[220:221], off
	s_waitcnt vmcnt(8)
	s_waitcnt lgkmcnt(0)
	s_barrier
	s_waitcnt lgkmcnt(0)
	v_mfma_f32_16x16x32_bf16 v[124:127], v[140:143], v[178:181], v[124:127]
	v_mfma_f32_16x16x32_bf16 v[120:123], v[154:157], v[178:181], v[120:123]
	v_mfma_f32_16x16x32_bf16 v[112:115], v[140:143], v[186:189], v[112:115]
	v_mfma_f32_16x16x32_bf16 v[108:111], v[154:157], v[186:189], v[108:111]
	v_mfma_f32_16x16x32_bf16 v[96:99], v[140:143], v[194:197], v[96:99]
	v_mfma_f32_16x16x32_bf16 v[92:95], v[154:157], v[194:197], v[92:95]
	v_mfma_f32_16x16x32_bf16 v[80:83], v[140:143], v[202:205], v[80:83]
	v_mfma_f32_16x16x32_bf16 v[76:79], v[154:157], v[202:205], v[76:79]
	v_mfma_f32_16x16x32_bf16 v[124:127], v[150:153], v[182:185], v[124:127]
	v_mfma_f32_16x16x32_bf16 v[120:123], v[158:161], v[182:185], v[120:123]
	v_mfma_f32_16x16x32_bf16 v[112:115], v[150:153], v[190:193], v[112:115]
	v_mfma_f32_16x16x32_bf16 v[108:111], v[158:161], v[190:193], v[108:111]
	v_mfma_f32_16x16x32_bf16 v[96:99], v[150:153], v[198:201], v[96:99]
	v_mfma_f32_16x16x32_bf16 v[92:95], v[158:161], v[198:201], v[92:95]
	v_mfma_f32_16x16x32_bf16 v[80:83], v[150:153], v[206:209], v[80:83]
	v_mfma_f32_16x16x32_bf16 v[76:79], v[158:161], v[206:209], v[76:79]
	v_mfma_f32_16x16x32_bf16 v[116:119], v[162:165], v[178:181], v[116:119]
	v_mfma_f32_16x16x32_bf16 v[104:107], v[170:173], v[178:181], v[104:107]
	v_mfma_f32_16x16x32_bf16 v[100:103], v[162:165], v[186:189], v[100:103]
	v_mfma_f32_16x16x32_bf16 v[88:91], v[170:173], v[186:189], v[88:91]
	v_mfma_f32_16x16x32_bf16 v[84:87], v[162:165], v[194:197], v[84:87]
	v_mfma_f32_16x16x32_bf16 v[72:75], v[170:173], v[194:197], v[72:75]
	v_mfma_f32_16x16x32_bf16 v[68:71], v[162:165], v[202:205], v[68:71]
	v_mfma_f32_16x16x32_bf16 v[64:67], v[170:173], v[202:205], v[64:67]
	v_mfma_f32_16x16x32_bf16 v[116:119], v[166:169], v[182:185], v[116:119]
	v_mfma_f32_16x16x32_bf16 v[104:107], v[174:177], v[182:185], v[104:107]
	v_mfma_f32_16x16x32_bf16 v[100:103], v[166:169], v[190:193], v[100:103]
	v_mfma_f32_16x16x32_bf16 v[88:91], v[174:177], v[190:193], v[88:91]
	v_mfma_f32_16x16x32_bf16 v[84:87], v[166:169], v[198:201], v[84:87]
	v_mfma_f32_16x16x32_bf16 v[72:75], v[174:177], v[198:201], v[72:75]
	v_mfma_f32_16x16x32_bf16 v[68:71], v[166:169], v[206:209], v[68:71]
	v_mfma_f32_16x16x32_bf16 v[64:67], v[174:177], v[206:209], v[64:67]
	s_barrier
	s_add_i32 s24, s46, s28
	v_lshl_add_u64 v[210:211], v[210:211], 0, s[4:5]
	s_mov_b32 m0, s24
	ds_read_b128 v[178:181], v149 offset:49152
	ds_read_b128 v[182:185], v149 offset:50176
	ds_read_b128 v[186:189], v149 offset:51200
	ds_read_b128 v[190:193], v149 offset:52224
	ds_read_b128 v[194:197], v149 offset:53248
	ds_read_b128 v[198:201], v149 offset:54272
	ds_read_b128 v[202:205], v149 offset:55296
	ds_read_b128 v[206:209], v149 offset:56320
	global_load_lds_dwordx4 v[210:211], off
	s_add_i32 m0, s24, 0x2000
	s_add_u32 s22, s22, 0x80080
	v_lshl_add_u64 v[210:211], v[214:215], 0, s[4:5]
	s_addc_u32 s23, s23, 0
	s_add_i32 s24, s47, s28
	global_load_lds_dwordx4 v[210:211], off
	v_lshl_add_u64 v[210:211], s[22:23], 0, v[128:129]
	s_mov_b32 m0, s24
	s_nop 0
	global_load_lds_dwordx4 v[210:211], off
	v_lshl_add_u64 v[210:211], s[22:23], 0, v[130:131]
	s_add_i32 m0, s24, 0x2000
	s_nop 0
	global_load_lds_dwordx4 v[210:211], off
	v_lshl_add_u64 v[210:211], v[216:217], 0, s[4:5]
	s_mov_b32 m0, s34
	s_nop 0
	global_load_lds_dwordx4 v[210:211], off
	v_lshl_add_u64 v[210:211], v[218:219], 0, s[4:5]
	s_mov_b32 m0, s35
	s_nop 0
	global_load_lds_dwordx4 v[210:211], off
	s_waitcnt vmcnt(8)
	s_waitcnt lgkmcnt(0)
	s_barrier
	s_waitcnt lgkmcnt(0)
	v_mfma_f32_16x16x32_bf16 v[60:63], v[140:143], v[178:181], v[60:63]
	v_mfma_f32_16x16x32_bf16 v[56:59], v[154:157], v[178:181], v[56:59]
	v_mfma_f32_16x16x32_bf16 v[48:51], v[140:143], v[186:189], v[48:51]
	v_mfma_f32_16x16x32_bf16 v[44:47], v[154:157], v[186:189], v[44:47]
	v_mfma_f32_16x16x32_bf16 v[32:35], v[140:143], v[194:197], v[32:35]
	v_mfma_f32_16x16x32_bf16 v[28:31], v[154:157], v[194:197], v[28:31]
	v_mfma_f32_16x16x32_bf16 v[16:19], v[140:143], v[202:205], v[16:19]
	v_mfma_f32_16x16x32_bf16 v[12:15], v[154:157], v[202:205], v[12:15]
	v_mfma_f32_16x16x32_bf16 v[60:63], v[150:153], v[182:185], v[60:63]
	v_mfma_f32_16x16x32_bf16 v[56:59], v[158:161], v[182:185], v[56:59]
	v_mfma_f32_16x16x32_bf16 v[48:51], v[150:153], v[190:193], v[48:51]
	v_mfma_f32_16x16x32_bf16 v[44:47], v[158:161], v[190:193], v[44:47]
	v_mfma_f32_16x16x32_bf16 v[32:35], v[150:153], v[198:201], v[32:35]
	v_mfma_f32_16x16x32_bf16 v[28:31], v[158:161], v[198:201], v[28:31]
	v_mfma_f32_16x16x32_bf16 v[16:19], v[150:153], v[206:209], v[16:19]
	v_mfma_f32_16x16x32_bf16 v[12:15], v[158:161], v[206:209], v[12:15]
	v_mfma_f32_16x16x32_bf16 v[52:55], v[162:165], v[178:181], v[52:55]
	v_mfma_f32_16x16x32_bf16 v[40:43], v[170:173], v[178:181], v[40:43]
	v_mfma_f32_16x16x32_bf16 v[36:39], v[162:165], v[186:189], v[36:39]
	v_mfma_f32_16x16x32_bf16 v[24:27], v[170:173], v[186:189], v[24:27]
	v_mfma_f32_16x16x32_bf16 v[20:23], v[162:165], v[194:197], v[20:23]
	v_mfma_f32_16x16x32_bf16 v[8:11], v[170:173], v[194:197], v[8:11]
	v_mfma_f32_16x16x32_bf16 v[4:7], v[162:165], v[202:205], v[4:7]
	v_mfma_f32_16x16x32_bf16 v[0:3], v[170:173], v[202:205], v[0:3]
	v_mfma_f32_16x16x32_bf16 v[52:55], v[166:169], v[182:185], v[52:55]
	v_mfma_f32_16x16x32_bf16 v[40:43], v[174:177], v[182:185], v[40:43]
	v_mfma_f32_16x16x32_bf16 v[36:39], v[166:169], v[190:193], v[36:39]
	v_mfma_f32_16x16x32_bf16 v[24:27], v[174:177], v[190:193], v[24:27]
	v_mfma_f32_16x16x32_bf16 v[20:23], v[166:169], v[198:201], v[20:23]
	v_mfma_f32_16x16x32_bf16 v[8:11], v[174:177], v[198:201], v[8:11]
	v_mfma_f32_16x16x32_bf16 v[4:7], v[166:169], v[206:209], v[4:7]
	v_mfma_f32_16x16x32_bf16 v[0:3], v[174:177], v[206:209], v[0:3]
	s_barrier
	s_add_i32 s45, s45, 2
	s_add_u32 s20, s20, 0x100
	s_addc_u32 s21, s21, 0
	s_add_u32 s43, s43, 0x100
	s_addc_u32 s44, s44, 0
	s_cmp_gt_u32 s45, 29
	s_cbranch_scc0 .LBB0_374
	s_and_b64 vcc, exec, s[6:7]
	s_cbranch_vccz .LBB0_377
	s_barrier

.LBB0_505:
	ds_read_b128 v[128:131], v151
	ds_read_b128 v[132:135], v151 offset:1024
	ds_read_b128 v[170:173], v151 offset:2048
	ds_read_b128 v[178:181], v151 offset:3072
	ds_read_b128 v[182:185], v153
	ds_read_b128 v[186:189], v153 offset:1024
	ds_read_b128 v[190:193], v153 offset:2048
	ds_read_b128 v[194:197], v153 offset:3072
	s_add_u32 s30, s4, 0xfff80080
	s_addc_u32 s31, s5, -1
	s_cmp_eq_u32 s39, 28
	s_cselect_b32 s35, s0, s31
	s_cselect_b32 s34, s21, s30
	s_cselect_b32 s31, s19, s38
	s_cselect_b32 s30, s36, s37
	v_lshl_add_u64 v[174:175], s[4:5], 0, v[160:161]
	s_add_i32 m0, s27, 0xc000
	ds_read_b128 v[198:201], v155
	ds_read_b128 v[202:205], v155 offset:1024
	ds_read_b128 v[206:209], v155 offset:2048
	ds_read_b128 v[214:217], v155 offset:3072
	ds_read_b128 v[218:221], v155 offset:4096
	ds_read_b128 v[222:225], v155 offset:5120
	ds_read_b128 v[226:229], v155 offset:6144
	ds_read_b128 v[230:233], v155 offset:7168
	global_load_lds_dwordx4 v[174:175], off
	v_lshl_add_u64 v[174:175], s[4:5], 0, v[162:163]
	s_add_i32 m0, s27, 0xe000
	s_nop 0
	global_load_lds_dwordx4 v[174:175], off
	s_waitcnt vmcnt(8)
	s_waitcnt lgkmcnt(0)
	s_barrier
	s_waitcnt lgkmcnt(0)
	v_mfma_f32_16x16x32_bf16 v[124:127], v[128:131], v[198:201], v[124:127]
	v_mfma_f32_16x16x32_bf16 v[120:123], v[170:173], v[198:201], v[120:123]
	v_mfma_f32_16x16x32_bf16 v[108:111], v[128:131], v[206:209], v[108:111]
	v_mfma_f32_16x16x32_bf16 v[104:107], v[170:173], v[206:209], v[104:107]
	v_mfma_f32_16x16x32_bf16 v[92:95], v[128:131], v[218:221], v[92:95]
	v_mfma_f32_16x16x32_bf16 v[88:91], v[170:173], v[218:221], v[88:91]
	v_mfma_f32_16x16x32_bf16 v[76:79], v[128:131], v[226:229], v[76:79]
	v_mfma_f32_16x16x32_bf16 v[72:75], v[170:173], v[226:229], v[72:75]
	v_mfma_f32_16x16x32_bf16 v[124:127], v[132:135], v[202:205], v[124:127]
	v_mfma_f32_16x16x32_bf16 v[120:123], v[178:181], v[202:205], v[120:123]
	v_mfma_f32_16x16x32_bf16 v[108:111], v[132:135], v[214:217], v[108:111]
	v_mfma_f32_16x16x32_bf16 v[104:107], v[178:181], v[214:217], v[104:107]
	v_mfma_f32_16x16x32_bf16 v[92:95], v[132:135], v[222:225], v[92:95]
	v_mfma_f32_16x16x32_bf16 v[88:91], v[178:181], v[222:225], v[88:91]
	v_mfma_f32_16x16x32_bf16 v[76:79], v[132:135], v[230:233], v[76:79]
	v_mfma_f32_16x16x32_bf16 v[72:75], v[178:181], v[230:233], v[72:75]
	v_mfma_f32_16x16x32_bf16 v[116:119], v[182:185], v[198:201], v[116:119]
	v_mfma_f32_16x16x32_bf16 v[112:115], v[190:193], v[198:201], v[112:115]
	v_mfma_f32_16x16x32_bf16 v[100:103], v[182:185], v[206:209], v[100:103]
	v_mfma_f32_16x16x32_bf16 v[96:99], v[190:193], v[206:209], v[96:99]
	v_mfma_f32_16x16x32_bf16 v[84:87], v[182:185], v[218:221], v[84:87]
	v_mfma_f32_16x16x32_bf16 v[80:83], v[190:193], v[218:221], v[80:83]
	v_mfma_f32_16x16x32_bf16 v[68:71], v[182:185], v[226:229], v[68:71]
	v_mfma_f32_16x16x32_bf16 v[64:67], v[190:193], v[226:229], v[64:67]
	v_mfma_f32_16x16x32_bf16 v[116:119], v[186:189], v[202:205], v[116:119]
	v_mfma_f32_16x16x32_bf16 v[112:115], v[194:197], v[202:205], v[112:115]
	v_mfma_f32_16x16x32_bf16 v[100:103], v[186:189], v[214:217], v[100:103]
	v_mfma_f32_16x16x32_bf16 v[96:99], v[194:197], v[214:217], v[96:99]
	v_mfma_f32_16x16x32_bf16 v[84:87], v[186:189], v[222:225], v[84:87]
	v_mfma_f32_16x16x32_bf16 v[80:83], v[194:197], v[222:225], v[80:83]
	v_mfma_f32_16x16x32_bf16 v[68:71], v[186:189], v[230:233], v[68:71]
	v_mfma_f32_16x16x32_bf16 v[64:67], v[194:197], v[230:233], v[64:67]
	s_barrier
	s_add_i32 s58, s55, s40
	v_lshl_add_u64 v[174:175], s[30:31], 0, v[138:139]
	s_mov_b32 m0, s58
	ds_read_b128 v[198:201], v155 offset:16384
	ds_read_b128 v[202:205], v155 offset:17408
	ds_read_b128 v[206:209], v155 offset:18432
	ds_read_b128 v[214:217], v155 offset:19456
	ds_read_b128 v[218:221], v155 offset:20480
	ds_read_b128 v[222:225], v155 offset:21504
	ds_read_b128 v[226:229], v155 offset:22528
	ds_read_b128 v[230:233], v155 offset:23552
	global_load_lds_dwordx4 v[174:175], off
	s_add_i32 m0, s58, 0x2000
	s_add_u32 s58, s30, 0x80000
	v_lshl_add_u64 v[210:211], s[30:31], 0, v[142:143]
	s_addc_u32 s59, s31, 0
	s_add_i32 s60, s56, s40
	global_load_lds_dwordx4 v[210:211], off
	v_lshl_add_u64 v[234:235], s[58:59], 0, v[138:139]
	s_mov_b32 m0, s60
	v_lshl_add_u64 v[236:237], s[34:35], 0, v[140:141]
	global_load_lds_dwordx4 v[234:235], off
	v_lshl_add_u64 v[234:235], s[58:59], 0, v[142:143]
	s_add_i32 m0, s60, 0x2000
	s_nop 0
	global_load_lds_dwordx4 v[234:235], off
	v_lshl_add_u64 v[234:235], s[34:35], 0, v[136:137]
	s_mov_b32 m0, s27
	s_nop 0
	global_load_lds_dwordx4 v[234:235], off
	s_mov_b32 m0, s29
	s_nop 0
	global_load_lds_dwordx4 v[236:237], off
	s_waitcnt vmcnt(8)
	s_waitcnt lgkmcnt(0)
	s_barrier
	s_waitcnt lgkmcnt(0)
	v_mfma_f32_16x16x32_bf16 v[60:63], v[128:131], v[198:201], v[60:63]
	v_mfma_f32_16x16x32_bf16 v[56:59], v[170:173], v[198:201], v[56:59]
	v_mfma_f32_16x16x32_bf16 v[44:47], v[128:131], v[206:209], v[44:47]
	v_mfma_f32_16x16x32_bf16 v[40:43], v[170:173], v[206:209], v[40:43]
	v_mfma_f32_16x16x32_bf16 v[28:31], v[128:131], v[218:221], v[28:31]
	v_mfma_f32_16x16x32_bf16 v[24:27], v[170:173], v[218:221], v[24:27]
	v_mfma_f32_16x16x32_bf16 v[12:15], v[128:131], v[226:229], v[12:15]
	v_mfma_f32_16x16x32_bf16 v[8:11], v[170:173], v[226:229], v[8:11]
	v_mfma_f32_16x16x32_bf16 v[60:63], v[132:135], v[202:205], v[60:63]
	v_mfma_f32_16x16x32_bf16 v[56:59], v[178:181], v[202:205], v[56:59]
	v_mfma_f32_16x16x32_bf16 v[44:47], v[132:135], v[214:217], v[44:47]
	v_mfma_f32_16x16x32_bf16 v[40:43], v[178:181], v[214:217], v[40:43]
	v_mfma_f32_16x16x32_bf16 v[28:31], v[132:135], v[222:225], v[28:31]
	v_mfma_f32_16x16x32_bf16 v[24:27], v[178:181], v[222:225], v[24:27]
	v_mfma_f32_16x16x32_bf16 v[12:15], v[132:135], v[230:233], v[12:15]
	v_mfma_f32_16x16x32_bf16 v[8:11], v[178:181], v[230:233], v[8:11]
	v_mfma_f32_16x16x32_bf16 v[52:55], v[182:185], v[198:201], v[52:55]
	v_mfma_f32_16x16x32_bf16 v[48:51], v[190:193], v[198:201], v[48:51]
	v_mfma_f32_16x16x32_bf16 v[36:39], v[182:185], v[206:209], v[36:39]
	v_mfma_f32_16x16x32_bf16 v[32:35], v[190:193], v[206:209], v[32:35]
	v_mfma_f32_16x16x32_bf16 v[20:23], v[182:185], v[218:221], v[20:23]
	v_mfma_f32_16x16x32_bf16 v[16:19], v[190:193], v[218:221], v[16:19]
	v_mfma_f32_16x16x32_bf16 v[4:7], v[182:185], v[226:229], v[4:7]
	v_mfma_f32_16x16x32_bf16 v[0:3], v[190:193], v[226:229], v[0:3]
	v_mfma_f32_16x16x32_bf16 v[52:55], v[186:189], v[202:205], v[52:55]
	v_mfma_f32_16x16x32_bf16 v[48:51], v[194:197], v[202:205], v[48:51]
	v_mfma_f32_16x16x32_bf16 v[36:39], v[186:189], v[214:217], v[36:39]
	v_mfma_f32_16x16x32_bf16 v[32:35], v[194:197], v[214:217], v[32:35]
	v_mfma_f32_16x16x32_bf16 v[20:23], v[186:189], v[222:225], v[20:23]
	v_mfma_f32_16x16x32_bf16 v[16:19], v[194:197], v[222:225], v[16:19]
	v_mfma_f32_16x16x32_bf16 v[4:7], v[186:189], v[230:233], v[4:7]
	v_mfma_f32_16x16x32_bf16 v[0:3], v[194:197], v[230:233], v[0:3]
	s_barrier
	s_add_i32 s58, 0, 0x18000
	v_add_u32_e32 v144, s58, v149
	s_add_i32 s59, 0, 0x1c000
	ds_read_b128 v[128:131], v144
	ds_read_b128 v[132:135], v144 offset:1024
	ds_read_b128 v[170:173], v144 offset:2048
	ds_read_b128 v[178:181], v144 offset:3072
	v_add_u32_e32 v144, s59, v149
	ds_read_b128 v[182:185], v144
	ds_read_b128 v[186:189], v144 offset:1024
	ds_read_b128 v[190:193], v144 offset:2048
	ds_read_b128 v[194:197], v144 offset:3072
	s_add_u32 s34, s34, 0x80000
	s_addc_u32 s35, s35, 0
	s_mov_b32 m0, s41
	v_lshl_add_u64 v[238:239], s[34:35], 0, v[136:137]
	ds_read_b128 v[198:201], v155 offset:32768
	ds_read_b128 v[202:205], v155 offset:33792
	ds_read_b128 v[206:209], v155 offset:34816
	ds_read_b128 v[214:217], v155 offset:35840
	ds_read_b128 v[218:221], v155 offset:36864
	ds_read_b128 v[222:225], v155 offset:37888
	ds_read_b128 v[226:229], v155 offset:38912
	ds_read_b128 v[230:233], v155 offset:39936
	global_load_lds_dwordx4 v[238:239], off
	v_lshl_add_u64 v[238:239], s[34:35], 0, v[140:141]
	s_mov_b32 m0, s42
	s_nop 0
	global_load_lds_dwordx4 v[238:239], off
	s_waitcnt vmcnt(8)
	s_waitcnt lgkmcnt(0)
	s_barrier
	s_waitcnt lgkmcnt(0)
	v_mfma_f32_16x16x32_bf16 v[124:127], v[128:131], v[198:201], v[124:127]
	v_mfma_f32_16x16x32_bf16 v[120:123], v[170:173], v[198:201], v[120:123]
	v_mfma_f32_16x16x32_bf16 v[108:111], v[128:131], v[206:209], v[108:111]
	v_mfma_f32_16x16x32_bf16 v[104:107], v[170:173], v[206:209], v[104:107]
	v_mfma_f32_16x16x32_bf16 v[92:95], v[128:131], v[218:221], v[92:95]
	v_mfma_f32_16x16x32_bf16 v[88:91], v[170:173], v[218:221], v[88:91]
	v_mfma_f32_16x16x32_bf16 v[76:79], v[128:131], v[226:229], v[76:79]
	v_mfma_f32_16x16x32_bf16 v[72:75], v[170:173], v[226:229], v[72:75]
	v_mfma_f32_16x16x32_bf16 v[124:127], v[132:135], v[202:205], v[124:127]
	v_mfma_f32_16x16x32_bf16 v[120:123], v[178:181], v[202:205], v[120:123]
	v_mfma_f32_16x16x32_bf16 v[108:111], v[132:135], v[214:217], v[108:111]
	v_mfma_f32_16x16x32_bf16 v[104:107], v[178:181], v[214:217], v[104:107]
	v_mfma_f32_16x16x32_bf16 v[92:95], v[132:135], v[222:225], v[92:95]
	v_mfma_f32_16x16x32_bf16 v[88:91], v[178:181], v[222:225], v[88:91]
	v_mfma_f32_16x16x32_bf16 v[76:79], v[132:135], v[230:233], v[76:79]
	v_mfma_f32_16x16x32_bf16 v[72:75], v[178:181], v[230:233], v[72:75]
	v_mfma_f32_16x16x32_bf16 v[116:119], v[182:185], v[198:201], v[116:119]
	v_mfma_f32_16x16x32_bf16 v[112:115], v[190:193], v[198:201], v[112:115]
	v_mfma_f32_16x16x32_bf16 v[100:103], v[182:185], v[206:209], v[100:103]
	v_mfma_f32_16x16x32_bf16 v[96:99], v[190:193], v[206:209], v[96:99]
	v_mfma_f32_16x16x32_bf16 v[84:87], v[182:185], v[218:221], v[84:87]
	v_mfma_f32_16x16x32_bf16 v[80:83], v[190:193], v[218:221], v[80:83]
	v_mfma_f32_16x16x32_bf16 v[68:71], v[182:185], v[226:229], v[68:71]
	v_mfma_f32_16x16x32_bf16 v[64:67], v[190:193], v[226:229], v[64:67]
	v_mfma_f32_16x16x32_bf16 v[116:119], v[186:189], v[202:205], v[116:119]
	v_mfma_f32_16x16x32_bf16 v[112:115], v[194:197], v[202:205], v[112:115]
	v_mfma_f32_16x16x32_bf16 v[100:103], v[186:189], v[214:217], v[100:103]
	v_mfma_f32_16x16x32_bf16 v[96:99], v[194:197], v[214:217], v[96:99]
	v_mfma_f32_16x16x32_bf16 v[84:87], v[186:189], v[222:225], v[84:87]
	v_mfma_f32_16x16x32_bf16 v[80:83], v[194:197], v[222:225], v[80:83]
	v_mfma_f32_16x16x32_bf16 v[68:71], v[186:189], v[230:233], v[68:71]
	v_mfma_f32_16x16x32_bf16 v[64:67], v[194:197], v[230:233], v[64:67]
	s_barrier
	s_add_i32 s34, s58, s40
	v_lshl_add_u64 v[174:175], v[174:175], 0, s[8:9]
	s_mov_b32 m0, s34
	ds_read_b128 v[198:201], v155 offset:49152
	ds_read_b128 v[202:205], v155 offset:50176
	ds_read_b128 v[206:209], v155 offset:51200
	ds_read_b128 v[214:217], v155 offset:52224
	ds_read_b128 v[218:221], v155 offset:53248
	ds_read_b128 v[222:225], v155 offset:54272
	ds_read_b128 v[226:229], v155 offset:55296
	ds_read_b128 v[230:233], v155 offset:56320
	global_load_lds_dwordx4 v[174:175], off
	s_add_i32 m0, s34, 0x2000
	s_add_u32 s30, s30, 0x80080
	v_lshl_add_u64 v[174:175], v[210:211], 0, s[8:9]
	s_addc_u32 s31, s31, 0
	s_add_i32 s34, s59, s40
	global_load_lds_dwordx4 v[174:175], off
	v_lshl_add_u64 v[174:175], s[30:31], 0, v[138:139]
	s_mov_b32 m0, s34
	s_nop 0
	global_load_lds_dwordx4 v[174:175], off
	v_lshl_add_u64 v[174:175], s[30:31], 0, v[142:143]
	s_add_i32 m0, s34, 0x2000
	s_nop 0
	global_load_lds_dwordx4 v[174:175], off
	v_lshl_add_u64 v[174:175], v[234:235], 0, s[8:9]
	s_mov_b32 m0, s44
	s_nop 0
	global_load_lds_dwordx4 v[174:175], off
	v_lshl_add_u64 v[174:175], v[236:237], 0, s[8:9]
	s_mov_b32 m0, s45
	s_nop 0
	global_load_lds_dwordx4 v[174:175], off
	s_waitcnt vmcnt(8)
	s_waitcnt lgkmcnt(0)
	s_barrier
	s_waitcnt lgkmcnt(0)
	v_mfma_f32_16x16x32_bf16 v[60:63], v[128:131], v[198:201], v[60:63]
	v_mfma_f32_16x16x32_bf16 v[56:59], v[170:173], v[198:201], v[56:59]
	v_mfma_f32_16x16x32_bf16 v[44:47], v[128:131], v[206:209], v[44:47]
	v_mfma_f32_16x16x32_bf16 v[40:43], v[170:173], v[206:209], v[40:43]
	v_mfma_f32_16x16x32_bf16 v[28:31], v[128:131], v[218:221], v[28:31]
	v_mfma_f32_16x16x32_bf16 v[24:27], v[170:173], v[218:221], v[24:27]
	v_mfma_f32_16x16x32_bf16 v[12:15], v[128:131], v[226:229], v[12:15]
	v_mfma_f32_16x16x32_bf16 v[8:11], v[170:173], v[226:229], v[8:11]
	v_mfma_f32_16x16x32_bf16 v[60:63], v[132:135], v[202:205], v[60:63]
	v_mfma_f32_16x16x32_bf16 v[56:59], v[178:181], v[202:205], v[56:59]
	v_mfma_f32_16x16x32_bf16 v[44:47], v[132:135], v[214:217], v[44:47]
	v_mfma_f32_16x16x32_bf16 v[40:43], v[178:181], v[214:217], v[40:43]
	v_mfma_f32_16x16x32_bf16 v[28:31], v[132:135], v[222:225], v[28:31]
	v_mfma_f32_16x16x32_bf16 v[24:27], v[178:181], v[222:225], v[24:27]
	v_mfma_f32_16x16x32_bf16 v[12:15], v[132:135], v[230:233], v[12:15]
	v_mfma_f32_16x16x32_bf16 v[8:11], v[178:181], v[230:233], v[8:11]
	v_mfma_f32_16x16x32_bf16 v[52:55], v[182:185], v[198:201], v[52:55]
	v_mfma_f32_16x16x32_bf16 v[48:51], v[190:193], v[198:201], v[48:51]
	v_mfma_f32_16x16x32_bf16 v[36:39], v[182:185], v[206:209], v[36:39]
	v_mfma_f32_16x16x32_bf16 v[32:35], v[190:193], v[206:209], v[32:35]
	v_mfma_f32_16x16x32_bf16 v[20:23], v[182:185], v[218:221], v[20:23]
	v_mfma_f32_16x16x32_bf16 v[16:19], v[190:193], v[218:221], v[16:19]
	v_mfma_f32_16x16x32_bf16 v[4:7], v[182:185], v[226:229], v[4:7]
	v_mfma_f32_16x16x32_bf16 v[0:3], v[190:193], v[226:229], v[0:3]
	v_mfma_f32_16x16x32_bf16 v[52:55], v[186:189], v[202:205], v[52:55]
	v_mfma_f32_16x16x32_bf16 v[48:51], v[194:197], v[202:205], v[48:51]
	v_mfma_f32_16x16x32_bf16 v[36:39], v[186:189], v[214:217], v[36:39]
	v_mfma_f32_16x16x32_bf16 v[32:35], v[194:197], v[214:217], v[32:35]
	v_mfma_f32_16x16x32_bf16 v[20:23], v[186:189], v[222:225], v[20:23]
	v_mfma_f32_16x16x32_bf16 v[16:19], v[194:197], v[222:225], v[16:19]
	v_mfma_f32_16x16x32_bf16 v[4:7], v[186:189], v[230:233], v[4:7]
	v_mfma_f32_16x16x32_bf16 v[0:3], v[194:197], v[230:233], v[0:3]
	s_barrier
	s_add_i32 s39, s39, 2
	s_add_u32 s4, s4, 0x100
	s_addc_u32 s5, s5, 0
	s_add_u32 s37, s37, 0x100
	s_addc_u32 s38, s38, 0
	s_cmp_gt_u32 s39, 29
	s_cbranch_scc0 .LBB0_505
	s_and_b64 vcc, exec, s[10:11]
	s_cbranch_vccz .LBB0_508
	s_barrier

.LBB0_736:
	ds_read_b128 v[140:143], v147
	ds_read_b128 v[150:153], v147 offset:1024
	ds_read_b128 v[154:157], v147 offset:2048
	ds_read_b128 v[158:161], v147 offset:3072
	ds_read_b128 v[162:165], v148
	ds_read_b128 v[166:169], v148 offset:1024
	ds_read_b128 v[170:173], v148 offset:2048
	ds_read_b128 v[174:177], v148 offset:3072
	s_add_u32 s22, s20, 0xfff80080
	s_addc_u32 s23, s21, -1
	s_cmp_eq_u32 s45, 28
	s_cselect_b32 s25, s11, s23
	s_cselect_b32 s24, s41, s22
	s_cselect_b32 s23, s9, s44
	s_cselect_b32 s22, s42, s43
	v_lshl_add_u64 v[210:211], s[20:21], 0, v[132:133]
	s_add_i32 m0, s19, 0xc000
	ds_read_b128 v[178:181], v149
	ds_read_b128 v[182:185], v149 offset:1024
	ds_read_b128 v[186:189], v149 offset:2048
	ds_read_b128 v[190:193], v149 offset:3072
	ds_read_b128 v[194:197], v149 offset:4096
	ds_read_b128 v[198:201], v149 offset:5120
	ds_read_b128 v[202:205], v149 offset:6144
	ds_read_b128 v[206:209], v149 offset:7168
	global_load_lds_dwordx4 v[210:211], off
	v_lshl_add_u64 v[210:211], s[20:21], 0, v[134:135]
	s_add_i32 m0, s19, 0xe000
	s_nop 0
	global_load_lds_dwordx4 v[210:211], off
	s_waitcnt vmcnt(8)
	s_waitcnt lgkmcnt(0)
	s_barrier
	s_waitcnt lgkmcnt(0)
	v_mfma_f32_16x16x32_bf16 v[124:127], v[140:143], v[178:181], v[124:127]
	v_mfma_f32_16x16x32_bf16 v[120:123], v[154:157], v[178:181], v[120:123]
	v_mfma_f32_16x16x32_bf16 v[116:119], v[140:143], v[186:189], v[116:119]
	v_mfma_f32_16x16x32_bf16 v[112:115], v[154:157], v[186:189], v[112:115]
	v_mfma_f32_16x16x32_bf16 v[92:95], v[140:143], v[194:197], v[92:95]
	v_mfma_f32_16x16x32_bf16 v[88:91], v[154:157], v[194:197], v[88:91]
	v_mfma_f32_16x16x32_bf16 v[84:87], v[140:143], v[202:205], v[84:87]
	v_mfma_f32_16x16x32_bf16 v[80:83], v[154:157], v[202:205], v[80:83]
	v_mfma_f32_16x16x32_bf16 v[124:127], v[150:153], v[182:185], v[124:127]
	v_mfma_f32_16x16x32_bf16 v[120:123], v[158:161], v[182:185], v[120:123]
	v_mfma_f32_16x16x32_bf16 v[116:119], v[150:153], v[190:193], v[116:119]
	v_mfma_f32_16x16x32_bf16 v[112:115], v[158:161], v[190:193], v[112:115]
	v_mfma_f32_16x16x32_bf16 v[92:95], v[150:153], v[198:201], v[92:95]
	v_mfma_f32_16x16x32_bf16 v[88:91], v[158:161], v[198:201], v[88:91]
	v_mfma_f32_16x16x32_bf16 v[84:87], v[150:153], v[206:209], v[84:87]
	v_mfma_f32_16x16x32_bf16 v[80:83], v[158:161], v[206:209], v[80:83]
	v_mfma_f32_16x16x32_bf16 v[108:111], v[162:165], v[178:181], v[108:111]
	v_mfma_f32_16x16x32_bf16 v[104:107], v[170:173], v[178:181], v[104:107]
	v_mfma_f32_16x16x32_bf16 v[100:103], v[162:165], v[186:189], v[100:103]
	v_mfma_f32_16x16x32_bf16 v[96:99], v[170:173], v[186:189], v[96:99]
	v_mfma_f32_16x16x32_bf16 v[76:79], v[162:165], v[194:197], v[76:79]
	v_mfma_f32_16x16x32_bf16 v[72:75], v[170:173], v[194:197], v[72:75]
	v_mfma_f32_16x16x32_bf16 v[68:71], v[162:165], v[202:205], v[68:71]
	v_mfma_f32_16x16x32_bf16 v[64:67], v[170:173], v[202:205], v[64:67]
	v_mfma_f32_16x16x32_bf16 v[108:111], v[166:169], v[182:185], v[108:111]
	v_mfma_f32_16x16x32_bf16 v[104:107], v[174:177], v[182:185], v[104:107]
	v_mfma_f32_16x16x32_bf16 v[100:103], v[166:169], v[190:193], v[100:103]
	v_mfma_f32_16x16x32_bf16 v[96:99], v[174:177], v[190:193], v[96:99]
	v_mfma_f32_16x16x32_bf16 v[76:79], v[166:169], v[198:201], v[76:79]
	v_mfma_f32_16x16x32_bf16 v[72:75], v[174:177], v[198:201], v[72:75]
	v_mfma_f32_16x16x32_bf16 v[68:71], v[166:169], v[206:209], v[68:71]
	v_mfma_f32_16x16x32_bf16 v[64:67], v[174:177], v[206:209], v[64:67]
	s_barrier
	s_add_i32 s46, s38, s28
	v_lshl_add_u64 v[210:211], s[22:23], 0, v[128:129]
	s_mov_b32 m0, s46
	ds_read_b128 v[178:181], v149 offset:16384
	ds_read_b128 v[182:185], v149 offset:17408
	ds_read_b128 v[186:189], v149 offset:18432
	ds_read_b128 v[190:193], v149 offset:19456
	ds_read_b128 v[194:197], v149 offset:20480
	ds_read_b128 v[198:201], v149 offset:21504
	ds_read_b128 v[202:205], v149 offset:22528
	ds_read_b128 v[206:209], v149 offset:23552
	global_load_lds_dwordx4 v[210:211], off
	s_add_i32 m0, s46, 0x2000
	s_add_u32 s46, s22, 0x80000
	v_lshl_add_u64 v[214:215], s[22:23], 0, v[130:131]
	s_addc_u32 s47, s23, 0
	s_add_i32 s48, s39, s28
	global_load_lds_dwordx4 v[214:215], off
	v_lshl_add_u64 v[216:217], s[46:47], 0, v[128:129]
	s_mov_b32 m0, s48
	v_lshl_add_u64 v[218:219], s[24:25], 0, v[130:131]
	global_load_lds_dwordx4 v[216:217], off
	v_lshl_add_u64 v[216:217], s[46:47], 0, v[130:131]
	s_add_i32 m0, s48, 0x2000
	s_nop 0
	global_load_lds_dwordx4 v[216:217], off
	v_lshl_add_u64 v[216:217], s[24:25], 0, v[128:129]
	s_mov_b32 m0, s19
	s_nop 0
	global_load_lds_dwordx4 v[216:217], off
	s_mov_b32 m0, s29
	s_nop 0
	global_load_lds_dwordx4 v[218:219], off
	s_waitcnt vmcnt(8)
	s_waitcnt lgkmcnt(0)
	s_barrier
	s_waitcnt lgkmcnt(0)
	v_mfma_f32_16x16x32_bf16 v[60:63], v[140:143], v[178:181], v[60:63]
	v_mfma_f32_16x16x32_bf16 v[56:59], v[154:157], v[178:181], v[56:59]
	v_mfma_f32_16x16x32_bf16 v[52:55], v[140:143], v[186:189], v[52:55]
	v_mfma_f32_16x16x32_bf16 v[48:51], v[154:157], v[186:189], v[48:51]
	v_mfma_f32_16x16x32_bf16 v[28:31], v[140:143], v[194:197], v[28:31]
	v_mfma_f32_16x16x32_bf16 v[24:27], v[154:157], v[194:197], v[24:27]
	v_mfma_f32_16x16x32_bf16 v[20:23], v[140:143], v[202:205], v[20:23]
	v_mfma_f32_16x16x32_bf16 v[16:19], v[154:157], v[202:205], v[16:19]
	v_mfma_f32_16x16x32_bf16 v[60:63], v[150:153], v[182:185], v[60:63]
	v_mfma_f32_16x16x32_bf16 v[56:59], v[158:161], v[182:185], v[56:59]
	v_mfma_f32_16x16x32_bf16 v[52:55], v[150:153], v[190:193], v[52:55]
	v_mfma_f32_16x16x32_bf16 v[48:51], v[158:161], v[190:193], v[48:51]
	v_mfma_f32_16x16x32_bf16 v[28:31], v[150:153], v[198:201], v[28:31]
	v_mfma_f32_16x16x32_bf16 v[24:27], v[158:161], v[198:201], v[24:27]
	v_mfma_f32_16x16x32_bf16 v[20:23], v[150:153], v[206:209], v[20:23]
	v_mfma_f32_16x16x32_bf16 v[16:19], v[158:161], v[206:209], v[16:19]
	v_mfma_f32_16x16x32_bf16 v[44:47], v[162:165], v[178:181], v[44:47]
	v_mfma_f32_16x16x32_bf16 v[40:43], v[170:173], v[178:181], v[40:43]
	v_mfma_f32_16x16x32_bf16 v[36:39], v[162:165], v[186:189], v[36:39]
	v_mfma_f32_16x16x32_bf16 v[32:35], v[170:173], v[186:189], v[32:35]
	v_mfma_f32_16x16x32_bf16 v[12:15], v[162:165], v[194:197], v[12:15]
	v_mfma_f32_16x16x32_bf16 v[8:11], v[170:173], v[194:197], v[8:11]
	v_mfma_f32_16x16x32_bf16 v[4:7], v[162:165], v[202:205], v[4:7]
	v_mfma_f32_16x16x32_bf16 v[0:3], v[170:173], v[202:205], v[0:3]
	v_mfma_f32_16x16x32_bf16 v[44:47], v[166:169], v[182:185], v[44:47]
	v_mfma_f32_16x16x32_bf16 v[40:43], v[174:177], v[182:185], v[40:43]
	v_mfma_f32_16x16x32_bf16 v[36:39], v[166:169], v[190:193], v[36:39]
	v_mfma_f32_16x16x32_bf16 v[32:35], v[174:177], v[190:193], v[32:35]
	v_mfma_f32_16x16x32_bf16 v[12:15], v[166:169], v[198:201], v[12:15]
	v_mfma_f32_16x16x32_bf16 v[8:11], v[174:177], v[198:201], v[8:11]
	v_mfma_f32_16x16x32_bf16 v[4:7], v[166:169], v[206:209], v[4:7]
	v_mfma_f32_16x16x32_bf16 v[0:3], v[174:177], v[206:209], v[0:3]
	s_barrier
	s_add_i32 s46, 0, 0x18000
	s_add_i32 s47, 0, 0x1c000
	v_add_u32_e32 v158, s46, v145
	v_add_u32_e32 v174, s47, v145
	ds_read_b128 v[140:143], v158
	ds_read_b128 v[150:153], v158 offset:1024
	ds_read_b128 v[154:157], v158 offset:2048
	ds_read_b128 v[158:161], v158 offset:3072
	ds_read_b128 v[162:165], v174
	ds_read_b128 v[166:169], v174 offset:1024
	ds_read_b128 v[170:173], v174 offset:2048
	ds_read_b128 v[174:177], v174 offset:3072
	s_add_u32 s24, s24, 0x80000
	s_addc_u32 s25, s25, 0
	s_mov_b32 m0, s30
	v_lshl_add_u64 v[220:221], s[24:25], 0, v[128:129]
	ds_read_b128 v[178:181], v149 offset:32768
	ds_read_b128 v[182:185], v149 offset:33792
	ds_read_b128 v[186:189], v149 offset:34816
	ds_read_b128 v[190:193], v149 offset:35840
	ds_read_b128 v[194:197], v149 offset:36864
	ds_read_b128 v[198:201], v149 offset:37888
	ds_read_b128 v[202:205], v149 offset:38912
	ds_read_b128 v[206:209], v149 offset:39936
	global_load_lds_dwordx4 v[220:221], off
	v_lshl_add_u64 v[220:221], s[24:25], 0, v[130:131]
	s_mov_b32 m0, s31
	s_nop 0
	global_load_lds_dwordx4 v[220:221], off
	s_waitcnt vmcnt(8)
	s_waitcnt lgkmcnt(0)
	s_barrier
	s_waitcnt lgkmcnt(0)
	v_mfma_f32_16x16x32_bf16 v[124:127], v[140:143], v[178:181], v[124:127]
	v_mfma_f32_16x16x32_bf16 v[120:123], v[154:157], v[178:181], v[120:123]
	v_mfma_f32_16x16x32_bf16 v[116:119], v[140:143], v[186:189], v[116:119]
	v_mfma_f32_16x16x32_bf16 v[112:115], v[154:157], v[186:189], v[112:115]
	v_mfma_f32_16x16x32_bf16 v[92:95], v[140:143], v[194:197], v[92:95]
	v_mfma_f32_16x16x32_bf16 v[88:91], v[154:157], v[194:197], v[88:91]
	v_mfma_f32_16x16x32_bf16 v[84:87], v[140:143], v[202:205], v[84:87]
	v_mfma_f32_16x16x32_bf16 v[80:83], v[154:157], v[202:205], v[80:83]
	v_mfma_f32_16x16x32_bf16 v[124:127], v[150:153], v[182:185], v[124:127]
	v_mfma_f32_16x16x32_bf16 v[120:123], v[158:161], v[182:185], v[120:123]
	v_mfma_f32_16x16x32_bf16 v[116:119], v[150:153], v[190:193], v[116:119]
	v_mfma_f32_16x16x32_bf16 v[112:115], v[158:161], v[190:193], v[112:115]
	v_mfma_f32_16x16x32_bf16 v[92:95], v[150:153], v[198:201], v[92:95]
	v_mfma_f32_16x16x32_bf16 v[88:91], v[158:161], v[198:201], v[88:91]
	v_mfma_f32_16x16x32_bf16 v[84:87], v[150:153], v[206:209], v[84:87]
	v_mfma_f32_16x16x32_bf16 v[80:83], v[158:161], v[206:209], v[80:83]
	v_mfma_f32_16x16x32_bf16 v[108:111], v[162:165], v[178:181], v[108:111]
	v_mfma_f32_16x16x32_bf16 v[104:107], v[170:173], v[178:181], v[104:107]
	v_mfma_f32_16x16x32_bf16 v[100:103], v[162:165], v[186:189], v[100:103]
	v_mfma_f32_16x16x32_bf16 v[96:99], v[170:173], v[186:189], v[96:99]
	v_mfma_f32_16x16x32_bf16 v[76:79], v[162:165], v[194:197], v[76:79]
	v_mfma_f32_16x16x32_bf16 v[72:75], v[170:173], v[194:197], v[72:75]
	v_mfma_f32_16x16x32_bf16 v[68:71], v[162:165], v[202:205], v[68:71]
	v_mfma_f32_16x16x32_bf16 v[64:67], v[170:173], v[202:205], v[64:67]
	v_mfma_f32_16x16x32_bf16 v[108:111], v[166:169], v[182:185], v[108:111]
	v_mfma_f32_16x16x32_bf16 v[104:107], v[174:177], v[182:185], v[104:107]
	v_mfma_f32_16x16x32_bf16 v[100:103], v[166:169], v[190:193], v[100:103]
	v_mfma_f32_16x16x32_bf16 v[96:99], v[174:177], v[190:193], v[96:99]
	v_mfma_f32_16x16x32_bf16 v[76:79], v[166:169], v[198:201], v[76:79]
	v_mfma_f32_16x16x32_bf16 v[72:75], v[174:177], v[198:201], v[72:75]
	v_mfma_f32_16x16x32_bf16 v[68:71], v[166:169], v[206:209], v[68:71]
	v_mfma_f32_16x16x32_bf16 v[64:67], v[174:177], v[206:209], v[64:67]
	s_barrier
	s_add_i32 s24, s46, s28
	v_lshl_add_u64 v[210:211], v[210:211], 0, s[4:5]
	s_mov_b32 m0, s24
	ds_read_b128 v[178:181], v149 offset:49152
	ds_read_b128 v[182:185], v149 offset:50176
	ds_read_b128 v[186:189], v149 offset:51200
	ds_read_b128 v[190:193], v149 offset:52224
	ds_read_b128 v[194:197], v149 offset:53248
	ds_read_b128 v[198:201], v149 offset:54272
	ds_read_b128 v[202:205], v149 offset:55296
	ds_read_b128 v[206:209], v149 offset:56320
	global_load_lds_dwordx4 v[210:211], off
	s_add_i32 m0, s24, 0x2000
	s_add_u32 s22, s22, 0x80080
	v_lshl_add_u64 v[210:211], v[214:215], 0, s[4:5]
	s_addc_u32 s23, s23, 0
	s_add_i32 s24, s47, s28
	global_load_lds_dwordx4 v[210:211], off
	v_lshl_add_u64 v[210:211], s[22:23], 0, v[128:129]
	s_mov_b32 m0, s24
	s_nop 0
	global_load_lds_dwordx4 v[210:211], off
	v_lshl_add_u64 v[210:211], s[22:23], 0, v[130:131]
	s_add_i32 m0, s24, 0x2000
	s_nop 0
	global_load_lds_dwordx4 v[210:211], off
	v_lshl_add_u64 v[210:211], v[216:217], 0, s[4:5]
	s_mov_b32 m0, s34
	s_nop 0
	global_load_lds_dwordx4 v[210:211], off
	v_lshl_add_u64 v[210:211], v[218:219], 0, s[4:5]
	s_mov_b32 m0, s35
	s_nop 0
	global_load_lds_dwordx4 v[210:211], off
	s_waitcnt vmcnt(8)
	s_waitcnt lgkmcnt(0)
	s_barrier
	s_waitcnt lgkmcnt(0)
	v_mfma_f32_16x16x32_bf16 v[60:63], v[140:143], v[178:181], v[60:63]
	v_mfma_f32_16x16x32_bf16 v[56:59], v[154:157], v[178:181], v[56:59]
	v_mfma_f32_16x16x32_bf16 v[52:55], v[140:143], v[186:189], v[52:55]
	v_mfma_f32_16x16x32_bf16 v[48:51], v[154:157], v[186:189], v[48:51]
	v_mfma_f32_16x16x32_bf16 v[28:31], v[140:143], v[194:197], v[28:31]
	v_mfma_f32_16x16x32_bf16 v[24:27], v[154:157], v[194:197], v[24:27]
	v_mfma_f32_16x16x32_bf16 v[20:23], v[140:143], v[202:205], v[20:23]
	v_mfma_f32_16x16x32_bf16 v[16:19], v[154:157], v[202:205], v[16:19]
	v_mfma_f32_16x16x32_bf16 v[60:63], v[150:153], v[182:185], v[60:63]
	v_mfma_f32_16x16x32_bf16 v[56:59], v[158:161], v[182:185], v[56:59]
	v_mfma_f32_16x16x32_bf16 v[52:55], v[150:153], v[190:193], v[52:55]
	v_mfma_f32_16x16x32_bf16 v[48:51], v[158:161], v[190:193], v[48:51]
	v_mfma_f32_16x16x32_bf16 v[28:31], v[150:153], v[198:201], v[28:31]
	v_mfma_f32_16x16x32_bf16 v[24:27], v[158:161], v[198:201], v[24:27]
	v_mfma_f32_16x16x32_bf16 v[20:23], v[150:153], v[206:209], v[20:23]
	v_mfma_f32_16x16x32_bf16 v[16:19], v[158:161], v[206:209], v[16:19]
	v_mfma_f32_16x16x32_bf16 v[44:47], v[162:165], v[178:181], v[44:47]
	v_mfma_f32_16x16x32_bf16 v[40:43], v[170:173], v[178:181], v[40:43]
	v_mfma_f32_16x16x32_bf16 v[36:39], v[162:165], v[186:189], v[36:39]
	v_mfma_f32_16x16x32_bf16 v[32:35], v[170:173], v[186:189], v[32:35]
	v_mfma_f32_16x16x32_bf16 v[12:15], v[162:165], v[194:197], v[12:15]
	v_mfma_f32_16x16x32_bf16 v[8:11], v[170:173], v[194:197], v[8:11]
	v_mfma_f32_16x16x32_bf16 v[4:7], v[162:165], v[202:205], v[4:7]
	v_mfma_f32_16x16x32_bf16 v[0:3], v[170:173], v[202:205], v[0:3]
	v_mfma_f32_16x16x32_bf16 v[44:47], v[166:169], v[182:185], v[44:47]
	v_mfma_f32_16x16x32_bf16 v[40:43], v[174:177], v[182:185], v[40:43]
	v_mfma_f32_16x16x32_bf16 v[36:39], v[166:169], v[190:193], v[36:39]
	v_mfma_f32_16x16x32_bf16 v[32:35], v[174:177], v[190:193], v[32:35]
	v_mfma_f32_16x16x32_bf16 v[12:15], v[166:169], v[198:201], v[12:15]
	v_mfma_f32_16x16x32_bf16 v[8:11], v[174:177], v[198:201], v[8:11]
	v_mfma_f32_16x16x32_bf16 v[4:7], v[166:169], v[206:209], v[4:7]
	v_mfma_f32_16x16x32_bf16 v[0:3], v[174:177], v[206:209], v[0:3]
	s_barrier
	s_add_i32 s45, s45, 2
	s_add_u32 s20, s20, 0x100
	s_addc_u32 s21, s21, 0
	s_add_u32 s43, s43, 0x100
	s_addc_u32 s44, s44, 0
	s_cmp_gt_u32 s45, 29
	s_cbranch_scc0 .LBB0_736
	s_and_b64 vcc, exec, s[6:7]
	s_cbranch_vccz .LBB0_739
	s_barrier

.LBB0_908:
	ds_read_b128 v[128:131], v149
	ds_read_b128 v[132:135], v149 offset:1024
	ds_read_b128 v[160:163], v149 offset:2048
	ds_read_b128 v[164:167], v149 offset:3072
	ds_read_b128 v[170:173], v151
	ds_read_b128 v[174:177], v151 offset:1024
	ds_read_b128 v[178:181], v151 offset:2048
	ds_read_b128 v[182:185], v151 offset:3072
	s_add_u32 s24, s22, 0xfff80080
	s_addc_u32 s25, s23, -1
	s_cmp_eq_u32 s31, 28
	s_cselect_b32 s27, s5, s25
	s_cselect_b32 s26, s15, s24
	s_cselect_b32 s25, s13, s30
	s_cselect_b32 s24, s28, s29
	v_lshl_add_u64 v[210:211], s[22:23], 0, v[152:153]
	s_add_i32 m0, s35, 0xc000
	ds_read_b128 v[186:189], v168
	ds_read_b128 v[190:193], v168 offset:1024
	ds_read_b128 v[194:197], v168 offset:2048
	ds_read_b128 v[198:201], v168 offset:3072
	ds_read_b128 v[202:205], v168 offset:4096
	ds_read_b128 v[206:209], v168 offset:5120
	ds_read_b128 v[214:217], v168 offset:6144
	ds_read_b128 v[218:221], v168 offset:7168
	global_load_lds_dwordx4 v[210:211], off
	v_lshl_add_u64 v[210:211], s[22:23], 0, v[154:155]
	s_add_i32 m0, s35, 0xe000
	s_nop 0
	global_load_lds_dwordx4 v[210:211], off
	s_waitcnt vmcnt(8)
	s_waitcnt lgkmcnt(0)
	s_barrier
	s_waitcnt lgkmcnt(0)
	v_mfma_f32_16x16x32_bf16 v[124:127], v[128:131], v[186:189], v[124:127]
	v_mfma_f32_16x16x32_bf16 v[120:123], v[160:163], v[186:189], v[120:123]
	v_mfma_f32_16x16x32_bf16 v[108:111], v[128:131], v[194:197], v[108:111]
	v_mfma_f32_16x16x32_bf16 v[104:107], v[160:163], v[194:197], v[104:107]
	v_mfma_f32_16x16x32_bf16 v[92:95], v[128:131], v[202:205], v[92:95]
	v_mfma_f32_16x16x32_bf16 v[88:91], v[160:163], v[202:205], v[88:91]
	v_mfma_f32_16x16x32_bf16 v[76:79], v[128:131], v[214:217], v[76:79]
	v_mfma_f32_16x16x32_bf16 v[72:75], v[160:163], v[214:217], v[72:75]
	v_mfma_f32_16x16x32_bf16 v[124:127], v[132:135], v[190:193], v[124:127]
	v_mfma_f32_16x16x32_bf16 v[120:123], v[164:167], v[190:193], v[120:123]
	v_mfma_f32_16x16x32_bf16 v[108:111], v[132:135], v[198:201], v[108:111]
	v_mfma_f32_16x16x32_bf16 v[104:107], v[164:167], v[198:201], v[104:107]
	v_mfma_f32_16x16x32_bf16 v[92:95], v[132:135], v[206:209], v[92:95]
	v_mfma_f32_16x16x32_bf16 v[88:91], v[164:167], v[206:209], v[88:91]
	v_mfma_f32_16x16x32_bf16 v[76:79], v[132:135], v[218:221], v[76:79]
	v_mfma_f32_16x16x32_bf16 v[72:75], v[164:167], v[218:221], v[72:75]
	v_mfma_f32_16x16x32_bf16 v[116:119], v[170:173], v[186:189], v[116:119]
	v_mfma_f32_16x16x32_bf16 v[112:115], v[178:181], v[186:189], v[112:115]
	v_mfma_f32_16x16x32_bf16 v[100:103], v[170:173], v[194:197], v[100:103]
	v_mfma_f32_16x16x32_bf16 v[96:99], v[178:181], v[194:197], v[96:99]
	v_mfma_f32_16x16x32_bf16 v[84:87], v[170:173], v[202:205], v[84:87]
	v_mfma_f32_16x16x32_bf16 v[80:83], v[178:181], v[202:205], v[80:83]
	v_mfma_f32_16x16x32_bf16 v[68:71], v[170:173], v[214:217], v[68:71]
	v_mfma_f32_16x16x32_bf16 v[64:67], v[178:181], v[214:217], v[64:67]
	v_mfma_f32_16x16x32_bf16 v[116:119], v[174:177], v[190:193], v[116:119]
	v_mfma_f32_16x16x32_bf16 v[112:115], v[182:185], v[190:193], v[112:115]
	v_mfma_f32_16x16x32_bf16 v[100:103], v[174:177], v[198:201], v[100:103]
	v_mfma_f32_16x16x32_bf16 v[96:99], v[182:185], v[198:201], v[96:99]
	v_mfma_f32_16x16x32_bf16 v[84:87], v[174:177], v[206:209], v[84:87]
	v_mfma_f32_16x16x32_bf16 v[80:83], v[182:185], v[206:209], v[80:83]
	v_mfma_f32_16x16x32_bf16 v[68:71], v[174:177], v[218:221], v[68:71]
	v_mfma_f32_16x16x32_bf16 v[64:67], v[182:185], v[218:221], v[64:67]
	s_barrier
	s_add_i32 s53, s46, s34
	v_lshl_add_u64 v[210:211], s[24:25], 0, v[138:139]
	s_mov_b32 m0, s53
	ds_read_b128 v[186:189], v168 offset:16384
	ds_read_b128 v[190:193], v168 offset:17408
	ds_read_b128 v[194:197], v168 offset:18432
	ds_read_b128 v[198:201], v168 offset:19456
	ds_read_b128 v[202:205], v168 offset:20480
	ds_read_b128 v[206:209], v168 offset:21504
	ds_read_b128 v[214:217], v168 offset:22528
	ds_read_b128 v[218:221], v168 offset:23552
	global_load_lds_dwordx4 v[210:211], off
	s_add_i32 m0, s53, 0x2000
	s_add_u32 s54, s24, 0x80000
	v_lshl_add_u64 v[222:223], s[24:25], 0, v[142:143]
	s_addc_u32 s55, s25, 0
	s_add_i32 s53, s47, s34
	global_load_lds_dwordx4 v[222:223], off
	v_lshl_add_u64 v[224:225], s[54:55], 0, v[138:139]
	s_mov_b32 m0, s53
	v_lshl_add_u64 v[226:227], s[26:27], 0, v[140:141]
	global_load_lds_dwordx4 v[224:225], off
	v_lshl_add_u64 v[224:225], s[54:55], 0, v[142:143]
	s_add_i32 m0, s53, 0x2000
	s_nop 0
	global_load_lds_dwordx4 v[224:225], off
	v_lshl_add_u64 v[224:225], s[26:27], 0, v[136:137]
	s_mov_b32 m0, s35
	s_nop 0
	global_load_lds_dwordx4 v[224:225], off
	s_mov_b32 m0, s36
	s_nop 0
	global_load_lds_dwordx4 v[226:227], off
	s_waitcnt vmcnt(8)
	s_waitcnt lgkmcnt(0)
	s_barrier
	s_waitcnt lgkmcnt(0)
	v_mfma_f32_16x16x32_bf16 v[60:63], v[128:131], v[186:189], v[60:63]
	v_mfma_f32_16x16x32_bf16 v[56:59], v[160:163], v[186:189], v[56:59]
	v_mfma_f32_16x16x32_bf16 v[44:47], v[128:131], v[194:197], v[44:47]
	v_mfma_f32_16x16x32_bf16 v[40:43], v[160:163], v[194:197], v[40:43]
	v_mfma_f32_16x16x32_bf16 v[28:31], v[128:131], v[202:205], v[28:31]
	v_mfma_f32_16x16x32_bf16 v[24:27], v[160:163], v[202:205], v[24:27]
	v_mfma_f32_16x16x32_bf16 v[12:15], v[128:131], v[214:217], v[12:15]
	v_mfma_f32_16x16x32_bf16 v[8:11], v[160:163], v[214:217], v[8:11]
	v_mfma_f32_16x16x32_bf16 v[60:63], v[132:135], v[190:193], v[60:63]
	v_mfma_f32_16x16x32_bf16 v[56:59], v[164:167], v[190:193], v[56:59]
	v_mfma_f32_16x16x32_bf16 v[44:47], v[132:135], v[198:201], v[44:47]
	v_mfma_f32_16x16x32_bf16 v[40:43], v[164:167], v[198:201], v[40:43]
	v_mfma_f32_16x16x32_bf16 v[28:31], v[132:135], v[206:209], v[28:31]
	v_mfma_f32_16x16x32_bf16 v[24:27], v[164:167], v[206:209], v[24:27]
	v_mfma_f32_16x16x32_bf16 v[12:15], v[132:135], v[218:221], v[12:15]
	v_mfma_f32_16x16x32_bf16 v[8:11], v[164:167], v[218:221], v[8:11]
	v_mfma_f32_16x16x32_bf16 v[52:55], v[170:173], v[186:189], v[52:55]
	v_mfma_f32_16x16x32_bf16 v[48:51], v[178:181], v[186:189], v[48:51]
	v_mfma_f32_16x16x32_bf16 v[36:39], v[170:173], v[194:197], v[36:39]
	v_mfma_f32_16x16x32_bf16 v[32:35], v[178:181], v[194:197], v[32:35]
	v_mfma_f32_16x16x32_bf16 v[20:23], v[170:173], v[202:205], v[20:23]
	v_mfma_f32_16x16x32_bf16 v[16:19], v[178:181], v[202:205], v[16:19]
	v_mfma_f32_16x16x32_bf16 v[4:7], v[170:173], v[214:217], v[4:7]
	v_mfma_f32_16x16x32_bf16 v[0:3], v[178:181], v[214:217], v[0:3]
	v_mfma_f32_16x16x32_bf16 v[52:55], v[174:177], v[190:193], v[52:55]
	v_mfma_f32_16x16x32_bf16 v[48:51], v[182:185], v[190:193], v[48:51]
	v_mfma_f32_16x16x32_bf16 v[36:39], v[174:177], v[198:201], v[36:39]
	v_mfma_f32_16x16x32_bf16 v[32:35], v[182:185], v[198:201], v[32:35]
	v_mfma_f32_16x16x32_bf16 v[20:23], v[174:177], v[206:209], v[20:23]
	v_mfma_f32_16x16x32_bf16 v[16:19], v[182:185], v[206:209], v[16:19]
	v_mfma_f32_16x16x32_bf16 v[4:7], v[174:177], v[218:221], v[4:7]
	v_mfma_f32_16x16x32_bf16 v[0:3], v[182:185], v[218:221], v[0:3]
	s_barrier
	s_add_i32 s53, 0, 0x18000
	v_add_u32_e32 v144, s53, v147
	s_add_i32 s54, 0, 0x1c000
	ds_read_b128 v[128:131], v144
	ds_read_b128 v[132:135], v144 offset:1024
	ds_read_b128 v[160:163], v144 offset:2048
	ds_read_b128 v[164:167], v144 offset:3072
	v_add_u32_e32 v144, s54, v147
	ds_read_b128 v[170:173], v144
	ds_read_b128 v[174:177], v144 offset:1024
	ds_read_b128 v[178:181], v144 offset:2048
	ds_read_b128 v[182:185], v144 offset:3072
	s_add_u32 s26, s26, 0x80000
	s_addc_u32 s27, s27, 0
	s_mov_b32 m0, s37
	v_lshl_add_u64 v[228:229], s[26:27], 0, v[136:137]
	ds_read_b128 v[186:189], v168 offset:32768
	ds_read_b128 v[190:193], v168 offset:33792
	ds_read_b128 v[194:197], v168 offset:34816
	ds_read_b128 v[198:201], v168 offset:35840
	ds_read_b128 v[202:205], v168 offset:36864
	ds_read_b128 v[206:209], v168 offset:37888
	ds_read_b128 v[214:217], v168 offset:38912
	ds_read_b128 v[218:221], v168 offset:39936
	global_load_lds_dwordx4 v[228:229], off
	v_lshl_add_u64 v[228:229], s[26:27], 0, v[140:141]
	s_mov_b32 m0, s38
	s_nop 0
	global_load_lds_dwordx4 v[228:229], off
	s_waitcnt vmcnt(8)
	s_waitcnt lgkmcnt(0)
	s_barrier
	s_waitcnt lgkmcnt(0)
	v_mfma_f32_16x16x32_bf16 v[124:127], v[128:131], v[186:189], v[124:127]
	v_mfma_f32_16x16x32_bf16 v[120:123], v[160:163], v[186:189], v[120:123]
	v_mfma_f32_16x16x32_bf16 v[108:111], v[128:131], v[194:197], v[108:111]
	v_mfma_f32_16x16x32_bf16 v[104:107], v[160:163], v[194:197], v[104:107]
	v_mfma_f32_16x16x32_bf16 v[92:95], v[128:131], v[202:205], v[92:95]
	v_mfma_f32_16x16x32_bf16 v[88:91], v[160:163], v[202:205], v[88:91]
	v_mfma_f32_16x16x32_bf16 v[76:79], v[128:131], v[214:217], v[76:79]
	v_mfma_f32_16x16x32_bf16 v[72:75], v[160:163], v[214:217], v[72:75]
	v_mfma_f32_16x16x32_bf16 v[124:127], v[132:135], v[190:193], v[124:127]
	v_mfma_f32_16x16x32_bf16 v[120:123], v[164:167], v[190:193], v[120:123]
	v_mfma_f32_16x16x32_bf16 v[108:111], v[132:135], v[198:201], v[108:111]
	v_mfma_f32_16x16x32_bf16 v[104:107], v[164:167], v[198:201], v[104:107]
	v_mfma_f32_16x16x32_bf16 v[92:95], v[132:135], v[206:209], v[92:95]
	v_mfma_f32_16x16x32_bf16 v[88:91], v[164:167], v[206:209], v[88:91]
	v_mfma_f32_16x16x32_bf16 v[76:79], v[132:135], v[218:221], v[76:79]
	v_mfma_f32_16x16x32_bf16 v[72:75], v[164:167], v[218:221], v[72:75]
	v_mfma_f32_16x16x32_bf16 v[116:119], v[170:173], v[186:189], v[116:119]
	v_mfma_f32_16x16x32_bf16 v[112:115], v[178:181], v[186:189], v[112:115]
	v_mfma_f32_16x16x32_bf16 v[100:103], v[170:173], v[194:197], v[100:103]
	v_mfma_f32_16x16x32_bf16 v[96:99], v[178:181], v[194:197], v[96:99]
	v_mfma_f32_16x16x32_bf16 v[84:87], v[170:173], v[202:205], v[84:87]
	v_mfma_f32_16x16x32_bf16 v[80:83], v[178:181], v[202:205], v[80:83]
	v_mfma_f32_16x16x32_bf16 v[68:71], v[170:173], v[214:217], v[68:71]
	v_mfma_f32_16x16x32_bf16 v[64:67], v[178:181], v[214:217], v[64:67]
	v_mfma_f32_16x16x32_bf16 v[116:119], v[174:177], v[190:193], v[116:119]
	v_mfma_f32_16x16x32_bf16 v[112:115], v[182:185], v[190:193], v[112:115]
	v_mfma_f32_16x16x32_bf16 v[100:103], v[174:177], v[198:201], v[100:103]
	v_mfma_f32_16x16x32_bf16 v[96:99], v[182:185], v[198:201], v[96:99]
	v_mfma_f32_16x16x32_bf16 v[84:87], v[174:177], v[206:209], v[84:87]
	v_mfma_f32_16x16x32_bf16 v[80:83], v[182:185], v[206:209], v[80:83]
	v_mfma_f32_16x16x32_bf16 v[68:71], v[174:177], v[218:221], v[68:71]
	v_mfma_f32_16x16x32_bf16 v[64:67], v[182:185], v[218:221], v[64:67]
	s_barrier
	s_add_i32 s26, s53, s34
	v_lshl_add_u64 v[210:211], v[210:211], 0, s[8:9]
	s_mov_b32 m0, s26
	ds_read_b128 v[186:189], v168 offset:49152
	ds_read_b128 v[190:193], v168 offset:50176
	ds_read_b128 v[194:197], v168 offset:51200
	ds_read_b128 v[198:201], v168 offset:52224
	ds_read_b128 v[202:205], v168 offset:53248
	ds_read_b128 v[206:209], v168 offset:54272
	ds_read_b128 v[214:217], v168 offset:55296
	ds_read_b128 v[218:221], v168 offset:56320
	global_load_lds_dwordx4 v[210:211], off
	s_add_i32 m0, s26, 0x2000
	s_add_u32 s24, s24, 0x80080
	v_lshl_add_u64 v[210:211], v[222:223], 0, s[8:9]
	s_addc_u32 s25, s25, 0
	s_add_i32 s26, s54, s34
	global_load_lds_dwordx4 v[210:211], off
	v_lshl_add_u64 v[210:211], s[24:25], 0, v[138:139]
	s_mov_b32 m0, s26
	s_nop 0
	global_load_lds_dwordx4 v[210:211], off
	v_lshl_add_u64 v[210:211], s[24:25], 0, v[142:143]
	s_add_i32 m0, s26, 0x2000
	s_nop 0
	global_load_lds_dwordx4 v[210:211], off
	v_lshl_add_u64 v[210:211], v[224:225], 0, s[8:9]
	s_mov_b32 m0, s39
	s_nop 0
	global_load_lds_dwordx4 v[210:211], off
	v_lshl_add_u64 v[210:211], v[226:227], 0, s[8:9]
	s_mov_b32 m0, s40
	s_nop 0
	global_load_lds_dwordx4 v[210:211], off
	s_waitcnt vmcnt(8)
	s_waitcnt lgkmcnt(0)
	s_barrier
	s_waitcnt lgkmcnt(0)
	v_mfma_f32_16x16x32_bf16 v[60:63], v[128:131], v[186:189], v[60:63]
	v_mfma_f32_16x16x32_bf16 v[56:59], v[160:163], v[186:189], v[56:59]
	v_mfma_f32_16x16x32_bf16 v[44:47], v[128:131], v[194:197], v[44:47]
	v_mfma_f32_16x16x32_bf16 v[40:43], v[160:163], v[194:197], v[40:43]
	v_mfma_f32_16x16x32_bf16 v[28:31], v[128:131], v[202:205], v[28:31]
	v_mfma_f32_16x16x32_bf16 v[24:27], v[160:163], v[202:205], v[24:27]
	v_mfma_f32_16x16x32_bf16 v[12:15], v[128:131], v[214:217], v[12:15]
	v_mfma_f32_16x16x32_bf16 v[8:11], v[160:163], v[214:217], v[8:11]
	v_mfma_f32_16x16x32_bf16 v[60:63], v[132:135], v[190:193], v[60:63]
	v_mfma_f32_16x16x32_bf16 v[56:59], v[164:167], v[190:193], v[56:59]
	v_mfma_f32_16x16x32_bf16 v[44:47], v[132:135], v[198:201], v[44:47]
	v_mfma_f32_16x16x32_bf16 v[40:43], v[164:167], v[198:201], v[40:43]
	v_mfma_f32_16x16x32_bf16 v[28:31], v[132:135], v[206:209], v[28:31]
	v_mfma_f32_16x16x32_bf16 v[24:27], v[164:167], v[206:209], v[24:27]
	v_mfma_f32_16x16x32_bf16 v[12:15], v[132:135], v[218:221], v[12:15]
	v_mfma_f32_16x16x32_bf16 v[8:11], v[164:167], v[218:221], v[8:11]
	v_mfma_f32_16x16x32_bf16 v[52:55], v[170:173], v[186:189], v[52:55]
	v_mfma_f32_16x16x32_bf16 v[48:51], v[178:181], v[186:189], v[48:51]
	v_mfma_f32_16x16x32_bf16 v[36:39], v[170:173], v[194:197], v[36:39]
	v_mfma_f32_16x16x32_bf16 v[32:35], v[178:181], v[194:197], v[32:35]
	v_mfma_f32_16x16x32_bf16 v[20:23], v[170:173], v[202:205], v[20:23]
	v_mfma_f32_16x16x32_bf16 v[16:19], v[178:181], v[202:205], v[16:19]
	v_mfma_f32_16x16x32_bf16 v[4:7], v[170:173], v[214:217], v[4:7]
	v_mfma_f32_16x16x32_bf16 v[0:3], v[178:181], v[214:217], v[0:3]
	v_mfma_f32_16x16x32_bf16 v[52:55], v[174:177], v[190:193], v[52:55]
	v_mfma_f32_16x16x32_bf16 v[48:51], v[182:185], v[190:193], v[48:51]
	v_mfma_f32_16x16x32_bf16 v[36:39], v[174:177], v[198:201], v[36:39]
	v_mfma_f32_16x16x32_bf16 v[32:35], v[182:185], v[198:201], v[32:35]
	v_mfma_f32_16x16x32_bf16 v[20:23], v[174:177], v[206:209], v[20:23]
	v_mfma_f32_16x16x32_bf16 v[16:19], v[182:185], v[206:209], v[16:19]
	v_mfma_f32_16x16x32_bf16 v[4:7], v[174:177], v[218:221], v[4:7]
	v_mfma_f32_16x16x32_bf16 v[0:3], v[182:185], v[218:221], v[0:3]
	s_barrier
	s_add_i32 s31, s31, 2
	s_add_u32 s22, s22, 0x100
	s_addc_u32 s23, s23, 0
	s_add_u32 s29, s29, 0x100
	s_addc_u32 s30, s30, 0
	s_cmp_gt_u32 s31, 29
	s_cbranch_scc0 .LBB0_908
	s_and_b64 vcc, exec, s[10:11]
	s_cbranch_vccz .LBB0_911
	s_barrier

.LBB0_1344:
	ds_read_b128 v[140:143], v147
	ds_read_b128 v[150:153], v147 offset:1024
	ds_read_b128 v[154:157], v147 offset:2048
	ds_read_b128 v[158:161], v147 offset:3072
	ds_read_b128 v[162:165], v148
	ds_read_b128 v[166:169], v148 offset:1024
	ds_read_b128 v[170:173], v148 offset:2048
	ds_read_b128 v[174:177], v148 offset:3072
	s_add_u32 s20, s18, 0xfff80080
	s_addc_u32 s21, s19, -1
	s_cmp_eq_u32 s44, 28
	s_cselect_b32 s23, s11, s21
	s_cselect_b32 s22, s40, s20
	s_cselect_b32 s21, s9, s43
	s_cselect_b32 s20, s41, s42
	v_lshl_add_u64 v[210:211], s[18:19], 0, v[132:133]
	s_add_i32 m0, s17, 0xc000
	ds_read_b128 v[178:181], v149
	ds_read_b128 v[182:185], v149 offset:1024
	ds_read_b128 v[186:189], v149 offset:2048
	ds_read_b128 v[190:193], v149 offset:3072
	ds_read_b128 v[194:197], v149 offset:4096
	ds_read_b128 v[198:201], v149 offset:5120
	ds_read_b128 v[202:205], v149 offset:6144
	ds_read_b128 v[206:209], v149 offset:7168
	global_load_lds_dwordx4 v[210:211], off
	v_lshl_add_u64 v[210:211], s[18:19], 0, v[134:135]
	s_add_i32 m0, s17, 0xe000
	s_nop 0
	global_load_lds_dwordx4 v[210:211], off
	s_waitcnt vmcnt(8)
	s_waitcnt lgkmcnt(0)
	s_barrier
	s_waitcnt lgkmcnt(0)
	v_mfma_f32_16x16x32_bf16 v[124:127], v[140:143], v[178:181], v[124:127]
	v_mfma_f32_16x16x32_bf16 v[120:123], v[154:157], v[178:181], v[120:123]
	v_mfma_f32_16x16x32_bf16 v[116:119], v[140:143], v[186:189], v[116:119]
	v_mfma_f32_16x16x32_bf16 v[112:115], v[154:157], v[186:189], v[112:115]
	v_mfma_f32_16x16x32_bf16 v[92:95], v[140:143], v[194:197], v[92:95]
	v_mfma_f32_16x16x32_bf16 v[88:91], v[154:157], v[194:197], v[88:91]
	v_mfma_f32_16x16x32_bf16 v[84:87], v[140:143], v[202:205], v[84:87]
	v_mfma_f32_16x16x32_bf16 v[80:83], v[154:157], v[202:205], v[80:83]
	v_mfma_f32_16x16x32_bf16 v[124:127], v[150:153], v[182:185], v[124:127]
	v_mfma_f32_16x16x32_bf16 v[120:123], v[158:161], v[182:185], v[120:123]
	v_mfma_f32_16x16x32_bf16 v[116:119], v[150:153], v[190:193], v[116:119]
	v_mfma_f32_16x16x32_bf16 v[112:115], v[158:161], v[190:193], v[112:115]
	v_mfma_f32_16x16x32_bf16 v[92:95], v[150:153], v[198:201], v[92:95]
	v_mfma_f32_16x16x32_bf16 v[88:91], v[158:161], v[198:201], v[88:91]
	v_mfma_f32_16x16x32_bf16 v[84:87], v[150:153], v[206:209], v[84:87]
	v_mfma_f32_16x16x32_bf16 v[80:83], v[158:161], v[206:209], v[80:83]
	v_mfma_f32_16x16x32_bf16 v[108:111], v[162:165], v[178:181], v[108:111]
	v_mfma_f32_16x16x32_bf16 v[104:107], v[170:173], v[178:181], v[104:107]
	v_mfma_f32_16x16x32_bf16 v[100:103], v[162:165], v[186:189], v[100:103]
	v_mfma_f32_16x16x32_bf16 v[96:99], v[170:173], v[186:189], v[96:99]
	v_mfma_f32_16x16x32_bf16 v[76:79], v[162:165], v[194:197], v[76:79]
	v_mfma_f32_16x16x32_bf16 v[72:75], v[170:173], v[194:197], v[72:75]
	v_mfma_f32_16x16x32_bf16 v[68:71], v[162:165], v[202:205], v[68:71]
	v_mfma_f32_16x16x32_bf16 v[64:67], v[170:173], v[202:205], v[64:67]
	v_mfma_f32_16x16x32_bf16 v[108:111], v[166:169], v[182:185], v[108:111]
	v_mfma_f32_16x16x32_bf16 v[104:107], v[174:177], v[182:185], v[104:107]
	v_mfma_f32_16x16x32_bf16 v[100:103], v[166:169], v[190:193], v[100:103]
	v_mfma_f32_16x16x32_bf16 v[96:99], v[174:177], v[190:193], v[96:99]
	v_mfma_f32_16x16x32_bf16 v[76:79], v[166:169], v[198:201], v[76:79]
	v_mfma_f32_16x16x32_bf16 v[72:75], v[174:177], v[198:201], v[72:75]
	v_mfma_f32_16x16x32_bf16 v[68:71], v[166:169], v[206:209], v[68:71]
	v_mfma_f32_16x16x32_bf16 v[64:67], v[174:177], v[206:209], v[64:67]
	s_barrier
	s_add_i32 s45, s37, s27
	v_lshl_add_u64 v[210:211], s[20:21], 0, v[128:129]
	s_mov_b32 m0, s45
	ds_read_b128 v[178:181], v149 offset:16384
	ds_read_b128 v[182:185], v149 offset:17408
	ds_read_b128 v[186:189], v149 offset:18432
	ds_read_b128 v[190:193], v149 offset:19456
	ds_read_b128 v[194:197], v149 offset:20480
	ds_read_b128 v[198:201], v149 offset:21504
	ds_read_b128 v[202:205], v149 offset:22528
	ds_read_b128 v[206:209], v149 offset:23552
	global_load_lds_dwordx4 v[210:211], off
	s_add_i32 m0, s45, 0x2000
	s_add_u32 s46, s20, 0x80000
	v_lshl_add_u64 v[214:215], s[20:21], 0, v[130:131]
	s_addc_u32 s47, s21, 0
	s_add_i32 s45, s38, s27
	global_load_lds_dwordx4 v[214:215], off
	v_lshl_add_u64 v[216:217], s[46:47], 0, v[128:129]
	s_mov_b32 m0, s45
	v_lshl_add_u64 v[218:219], s[22:23], 0, v[130:131]
	global_load_lds_dwordx4 v[216:217], off
	v_lshl_add_u64 v[216:217], s[46:47], 0, v[130:131]
	s_add_i32 m0, s45, 0x2000
	s_nop 0
	global_load_lds_dwordx4 v[216:217], off
	v_lshl_add_u64 v[216:217], s[22:23], 0, v[128:129]
	s_mov_b32 m0, s17
	s_nop 0
	global_load_lds_dwordx4 v[216:217], off
	s_mov_b32 m0, s28
	s_nop 0
	global_load_lds_dwordx4 v[218:219], off
	s_waitcnt vmcnt(8)
	s_waitcnt lgkmcnt(0)
	s_barrier
	s_waitcnt lgkmcnt(0)
	v_mfma_f32_16x16x32_bf16 v[60:63], v[140:143], v[178:181], v[60:63]
	v_mfma_f32_16x16x32_bf16 v[56:59], v[154:157], v[178:181], v[56:59]
	v_mfma_f32_16x16x32_bf16 v[52:55], v[140:143], v[186:189], v[52:55]
	v_mfma_f32_16x16x32_bf16 v[48:51], v[154:157], v[186:189], v[48:51]
	v_mfma_f32_16x16x32_bf16 v[28:31], v[140:143], v[194:197], v[28:31]
	v_mfma_f32_16x16x32_bf16 v[24:27], v[154:157], v[194:197], v[24:27]
	v_mfma_f32_16x16x32_bf16 v[20:23], v[140:143], v[202:205], v[20:23]
	v_mfma_f32_16x16x32_bf16 v[16:19], v[154:157], v[202:205], v[16:19]
	v_mfma_f32_16x16x32_bf16 v[60:63], v[150:153], v[182:185], v[60:63]
	v_mfma_f32_16x16x32_bf16 v[56:59], v[158:161], v[182:185], v[56:59]
	v_mfma_f32_16x16x32_bf16 v[52:55], v[150:153], v[190:193], v[52:55]
	v_mfma_f32_16x16x32_bf16 v[48:51], v[158:161], v[190:193], v[48:51]
	v_mfma_f32_16x16x32_bf16 v[28:31], v[150:153], v[198:201], v[28:31]
	v_mfma_f32_16x16x32_bf16 v[24:27], v[158:161], v[198:201], v[24:27]
	v_mfma_f32_16x16x32_bf16 v[20:23], v[150:153], v[206:209], v[20:23]
	v_mfma_f32_16x16x32_bf16 v[16:19], v[158:161], v[206:209], v[16:19]
	v_mfma_f32_16x16x32_bf16 v[44:47], v[162:165], v[178:181], v[44:47]
	v_mfma_f32_16x16x32_bf16 v[40:43], v[170:173], v[178:181], v[40:43]
	v_mfma_f32_16x16x32_bf16 v[36:39], v[162:165], v[186:189], v[36:39]
	v_mfma_f32_16x16x32_bf16 v[32:35], v[170:173], v[186:189], v[32:35]
	v_mfma_f32_16x16x32_bf16 v[12:15], v[162:165], v[194:197], v[12:15]
	v_mfma_f32_16x16x32_bf16 v[8:11], v[170:173], v[194:197], v[8:11]
	v_mfma_f32_16x16x32_bf16 v[4:7], v[162:165], v[202:205], v[4:7]
	v_mfma_f32_16x16x32_bf16 v[0:3], v[170:173], v[202:205], v[0:3]
	v_mfma_f32_16x16x32_bf16 v[44:47], v[166:169], v[182:185], v[44:47]
	v_mfma_f32_16x16x32_bf16 v[40:43], v[174:177], v[182:185], v[40:43]
	v_mfma_f32_16x16x32_bf16 v[36:39], v[166:169], v[190:193], v[36:39]
	v_mfma_f32_16x16x32_bf16 v[32:35], v[174:177], v[190:193], v[32:35]
	v_mfma_f32_16x16x32_bf16 v[12:15], v[166:169], v[198:201], v[12:15]
	v_mfma_f32_16x16x32_bf16 v[8:11], v[174:177], v[198:201], v[8:11]
	v_mfma_f32_16x16x32_bf16 v[4:7], v[166:169], v[206:209], v[4:7]
	v_mfma_f32_16x16x32_bf16 v[0:3], v[174:177], v[206:209], v[0:3]
	s_barrier
	s_add_i32 s45, 0, 0x18000
	s_add_i32 s46, 0, 0x1c000
	v_add_u32_e32 v158, s45, v145
	v_add_u32_e32 v174, s46, v145
	ds_read_b128 v[140:143], v158
	ds_read_b128 v[150:153], v158 offset:1024
	ds_read_b128 v[154:157], v158 offset:2048
	ds_read_b128 v[158:161], v158 offset:3072
	ds_read_b128 v[162:165], v174
	ds_read_b128 v[166:169], v174 offset:1024
	ds_read_b128 v[170:173], v174 offset:2048
	ds_read_b128 v[174:177], v174 offset:3072
	s_add_u32 s22, s22, 0x80000
	s_addc_u32 s23, s23, 0
	s_mov_b32 m0, s29
	v_lshl_add_u64 v[220:221], s[22:23], 0, v[128:129]
	ds_read_b128 v[178:181], v149 offset:32768
	ds_read_b128 v[182:185], v149 offset:33792
	ds_read_b128 v[186:189], v149 offset:34816
	ds_read_b128 v[190:193], v149 offset:35840
	ds_read_b128 v[194:197], v149 offset:36864
	ds_read_b128 v[198:201], v149 offset:37888
	ds_read_b128 v[202:205], v149 offset:38912
	ds_read_b128 v[206:209], v149 offset:39936
	global_load_lds_dwordx4 v[220:221], off
	v_lshl_add_u64 v[220:221], s[22:23], 0, v[130:131]
	s_mov_b32 m0, s30
	s_nop 0
	global_load_lds_dwordx4 v[220:221], off
	s_waitcnt vmcnt(8)
	s_waitcnt lgkmcnt(0)
	s_barrier
	s_waitcnt lgkmcnt(0)
	v_mfma_f32_16x16x32_bf16 v[124:127], v[140:143], v[178:181], v[124:127]
	v_mfma_f32_16x16x32_bf16 v[120:123], v[154:157], v[178:181], v[120:123]
	v_mfma_f32_16x16x32_bf16 v[116:119], v[140:143], v[186:189], v[116:119]
	v_mfma_f32_16x16x32_bf16 v[112:115], v[154:157], v[186:189], v[112:115]
	v_mfma_f32_16x16x32_bf16 v[92:95], v[140:143], v[194:197], v[92:95]
	v_mfma_f32_16x16x32_bf16 v[88:91], v[154:157], v[194:197], v[88:91]
	v_mfma_f32_16x16x32_bf16 v[84:87], v[140:143], v[202:205], v[84:87]
	v_mfma_f32_16x16x32_bf16 v[80:83], v[154:157], v[202:205], v[80:83]
	v_mfma_f32_16x16x32_bf16 v[124:127], v[150:153], v[182:185], v[124:127]
	v_mfma_f32_16x16x32_bf16 v[120:123], v[158:161], v[182:185], v[120:123]
	v_mfma_f32_16x16x32_bf16 v[116:119], v[150:153], v[190:193], v[116:119]
	v_mfma_f32_16x16x32_bf16 v[112:115], v[158:161], v[190:193], v[112:115]
	v_mfma_f32_16x16x32_bf16 v[92:95], v[150:153], v[198:201], v[92:95]
	v_mfma_f32_16x16x32_bf16 v[88:91], v[158:161], v[198:201], v[88:91]
	v_mfma_f32_16x16x32_bf16 v[84:87], v[150:153], v[206:209], v[84:87]
	v_mfma_f32_16x16x32_bf16 v[80:83], v[158:161], v[206:209], v[80:83]
	v_mfma_f32_16x16x32_bf16 v[108:111], v[162:165], v[178:181], v[108:111]
	v_mfma_f32_16x16x32_bf16 v[104:107], v[170:173], v[178:181], v[104:107]
	v_mfma_f32_16x16x32_bf16 v[100:103], v[162:165], v[186:189], v[100:103]
	v_mfma_f32_16x16x32_bf16 v[96:99], v[170:173], v[186:189], v[96:99]
	v_mfma_f32_16x16x32_bf16 v[76:79], v[162:165], v[194:197], v[76:79]
	v_mfma_f32_16x16x32_bf16 v[72:75], v[170:173], v[194:197], v[72:75]
	v_mfma_f32_16x16x32_bf16 v[68:71], v[162:165], v[202:205], v[68:71]
	v_mfma_f32_16x16x32_bf16 v[64:67], v[170:173], v[202:205], v[64:67]
	v_mfma_f32_16x16x32_bf16 v[108:111], v[166:169], v[182:185], v[108:111]
	v_mfma_f32_16x16x32_bf16 v[104:107], v[174:177], v[182:185], v[104:107]
	v_mfma_f32_16x16x32_bf16 v[100:103], v[166:169], v[190:193], v[100:103]
	v_mfma_f32_16x16x32_bf16 v[96:99], v[174:177], v[190:193], v[96:99]
	v_mfma_f32_16x16x32_bf16 v[76:79], v[166:169], v[198:201], v[76:79]
	v_mfma_f32_16x16x32_bf16 v[72:75], v[174:177], v[198:201], v[72:75]
	v_mfma_f32_16x16x32_bf16 v[68:71], v[166:169], v[206:209], v[68:71]
	v_mfma_f32_16x16x32_bf16 v[64:67], v[174:177], v[206:209], v[64:67]
	s_barrier
	s_add_i32 s22, s45, s27
	v_lshl_add_u64 v[210:211], v[210:211], 0, s[4:5]
	s_mov_b32 m0, s22
	ds_read_b128 v[178:181], v149 offset:49152
	ds_read_b128 v[182:185], v149 offset:50176
	ds_read_b128 v[186:189], v149 offset:51200
	ds_read_b128 v[190:193], v149 offset:52224
	ds_read_b128 v[194:197], v149 offset:53248
	ds_read_b128 v[198:201], v149 offset:54272
	ds_read_b128 v[202:205], v149 offset:55296
	ds_read_b128 v[206:209], v149 offset:56320
	global_load_lds_dwordx4 v[210:211], off
	s_add_i32 m0, s22, 0x2000
	s_add_u32 s20, s20, 0x80080
	v_lshl_add_u64 v[210:211], v[214:215], 0, s[4:5]
	s_addc_u32 s21, s21, 0
	s_add_i32 s22, s46, s27
	global_load_lds_dwordx4 v[210:211], off
	v_lshl_add_u64 v[210:211], s[20:21], 0, v[128:129]
	s_mov_b32 m0, s22
	s_nop 0
	global_load_lds_dwordx4 v[210:211], off
	v_lshl_add_u64 v[210:211], s[20:21], 0, v[130:131]
	s_add_i32 m0, s22, 0x2000
	s_nop 0
	global_load_lds_dwordx4 v[210:211], off
	v_lshl_add_u64 v[210:211], v[216:217], 0, s[4:5]
	s_mov_b32 m0, s33
	s_nop 0
	global_load_lds_dwordx4 v[210:211], off
	v_lshl_add_u64 v[210:211], v[218:219], 0, s[4:5]
	s_mov_b32 m0, s34
	s_nop 0
	global_load_lds_dwordx4 v[210:211], off
	s_waitcnt vmcnt(8)
	s_waitcnt lgkmcnt(0)
	s_barrier
	s_waitcnt lgkmcnt(0)
	v_mfma_f32_16x16x32_bf16 v[60:63], v[140:143], v[178:181], v[60:63]
	v_mfma_f32_16x16x32_bf16 v[56:59], v[154:157], v[178:181], v[56:59]
	v_mfma_f32_16x16x32_bf16 v[52:55], v[140:143], v[186:189], v[52:55]
	v_mfma_f32_16x16x32_bf16 v[48:51], v[154:157], v[186:189], v[48:51]
	v_mfma_f32_16x16x32_bf16 v[28:31], v[140:143], v[194:197], v[28:31]
	v_mfma_f32_16x16x32_bf16 v[24:27], v[154:157], v[194:197], v[24:27]
	v_mfma_f32_16x16x32_bf16 v[20:23], v[140:143], v[202:205], v[20:23]
	v_mfma_f32_16x16x32_bf16 v[16:19], v[154:157], v[202:205], v[16:19]
	v_mfma_f32_16x16x32_bf16 v[60:63], v[150:153], v[182:185], v[60:63]
	v_mfma_f32_16x16x32_bf16 v[56:59], v[158:161], v[182:185], v[56:59]
	v_mfma_f32_16x16x32_bf16 v[52:55], v[150:153], v[190:193], v[52:55]
	v_mfma_f32_16x16x32_bf16 v[48:51], v[158:161], v[190:193], v[48:51]
	v_mfma_f32_16x16x32_bf16 v[28:31], v[150:153], v[198:201], v[28:31]
	v_mfma_f32_16x16x32_bf16 v[24:27], v[158:161], v[198:201], v[24:27]
	v_mfma_f32_16x16x32_bf16 v[20:23], v[150:153], v[206:209], v[20:23]
	v_mfma_f32_16x16x32_bf16 v[16:19], v[158:161], v[206:209], v[16:19]
	v_mfma_f32_16x16x32_bf16 v[44:47], v[162:165], v[178:181], v[44:47]
	v_mfma_f32_16x16x32_bf16 v[40:43], v[170:173], v[178:181], v[40:43]
	v_mfma_f32_16x16x32_bf16 v[36:39], v[162:165], v[186:189], v[36:39]
	v_mfma_f32_16x16x32_bf16 v[32:35], v[170:173], v[186:189], v[32:35]
	v_mfma_f32_16x16x32_bf16 v[12:15], v[162:165], v[194:197], v[12:15]
	v_mfma_f32_16x16x32_bf16 v[8:11], v[170:173], v[194:197], v[8:11]
	v_mfma_f32_16x16x32_bf16 v[4:7], v[162:165], v[202:205], v[4:7]
	v_mfma_f32_16x16x32_bf16 v[0:3], v[170:173], v[202:205], v[0:3]
	v_mfma_f32_16x16x32_bf16 v[44:47], v[166:169], v[182:185], v[44:47]
	v_mfma_f32_16x16x32_bf16 v[40:43], v[174:177], v[182:185], v[40:43]
	v_mfma_f32_16x16x32_bf16 v[36:39], v[166:169], v[190:193], v[36:39]
	v_mfma_f32_16x16x32_bf16 v[32:35], v[174:177], v[190:193], v[32:35]
	v_mfma_f32_16x16x32_bf16 v[12:15], v[166:169], v[198:201], v[12:15]
	v_mfma_f32_16x16x32_bf16 v[8:11], v[174:177], v[198:201], v[8:11]
	v_mfma_f32_16x16x32_bf16 v[4:7], v[166:169], v[206:209], v[4:7]
	v_mfma_f32_16x16x32_bf16 v[0:3], v[174:177], v[206:209], v[0:3]
	s_barrier
	s_add_i32 s44, s44, 2
	s_add_u32 s18, s18, 0x100
	s_addc_u32 s19, s19, 0
	s_add_u32 s42, s42, 0x100
	s_addc_u32 s43, s43, 0
	s_cmp_gt_u32 s44, 29
	s_cbranch_scc0 .LBB0_1344
	s_and_b64 vcc, exec, s[6:7]
	s_cbranch_vccz .LBB0_1347
	s_barrier

.LBB0_1480:
	ds_read_b128 v[128:131], v149
	ds_read_b128 v[132:135], v149 offset:1024
	ds_read_b128 v[168:171], v149 offset:2048
	ds_read_b128 v[174:177], v149 offset:3072
	ds_read_b128 v[178:181], v172
	ds_read_b128 v[182:185], v172 offset:1024
	ds_read_b128 v[186:189], v172 offset:2048
	ds_read_b128 v[190:193], v172 offset:3072
	s_add_u32 s40, s38, 0xfff80080
	s_addc_u32 s41, s39, -1
	s_cmp_eq_u32 s45, 28
	s_cselect_b32 s43, s0, s41
	s_cselect_b32 s42, s5, s40
	s_cselect_b32 s41, s27, s44
	s_cselect_b32 s40, s29, s33
	v_lshl_add_u64 v[210:211], s[38:39], 0, v[154:155]
	s_add_i32 m0, s37, 0xc000
	ds_read_b128 v[194:197], v173
	ds_read_b128 v[198:201], v173 offset:1024
	ds_read_b128 v[202:205], v173 offset:2048
	ds_read_b128 v[206:209], v173 offset:3072
	ds_read_b128 v[214:217], v173 offset:4096
	ds_read_b128 v[218:221], v173 offset:5120
	ds_read_b128 v[222:225], v173 offset:6144
	ds_read_b128 v[226:229], v173 offset:7168
	global_load_lds_dwordx4 v[210:211], off
	v_lshl_add_u64 v[210:211], s[38:39], 0, v[156:157]
	s_add_i32 m0, s37, 0xe000
	s_nop 0
	global_load_lds_dwordx4 v[210:211], off
	s_waitcnt vmcnt(8)
	s_waitcnt lgkmcnt(0)
	s_barrier
	s_waitcnt lgkmcnt(0)
	v_mfma_f32_16x16x32_bf16 v[124:127], v[128:131], v[194:197], v[124:127]
	v_mfma_f32_16x16x32_bf16 v[120:123], v[168:171], v[194:197], v[120:123]
	v_mfma_f32_16x16x32_bf16 v[108:111], v[128:131], v[202:205], v[108:111]
	v_mfma_f32_16x16x32_bf16 v[104:107], v[168:171], v[202:205], v[104:107]
	v_mfma_f32_16x16x32_bf16 v[92:95], v[128:131], v[214:217], v[92:95]
	v_mfma_f32_16x16x32_bf16 v[88:91], v[168:171], v[214:217], v[88:91]
	v_mfma_f32_16x16x32_bf16 v[76:79], v[128:131], v[222:225], v[76:79]
	v_mfma_f32_16x16x32_bf16 v[72:75], v[168:171], v[222:225], v[72:75]
	v_mfma_f32_16x16x32_bf16 v[124:127], v[132:135], v[198:201], v[124:127]
	v_mfma_f32_16x16x32_bf16 v[120:123], v[174:177], v[198:201], v[120:123]
	v_mfma_f32_16x16x32_bf16 v[108:111], v[132:135], v[206:209], v[108:111]
	v_mfma_f32_16x16x32_bf16 v[104:107], v[174:177], v[206:209], v[104:107]
	v_mfma_f32_16x16x32_bf16 v[92:95], v[132:135], v[218:221], v[92:95]
	v_mfma_f32_16x16x32_bf16 v[88:91], v[174:177], v[218:221], v[88:91]
	v_mfma_f32_16x16x32_bf16 v[76:79], v[132:135], v[226:229], v[76:79]
	v_mfma_f32_16x16x32_bf16 v[72:75], v[174:177], v[226:229], v[72:75]
	v_mfma_f32_16x16x32_bf16 v[116:119], v[178:181], v[194:197], v[116:119]
	v_mfma_f32_16x16x32_bf16 v[112:115], v[186:189], v[194:197], v[112:115]
	v_mfma_f32_16x16x32_bf16 v[100:103], v[178:181], v[202:205], v[100:103]
	v_mfma_f32_16x16x32_bf16 v[96:99], v[186:189], v[202:205], v[96:99]
	v_mfma_f32_16x16x32_bf16 v[84:87], v[178:181], v[214:217], v[84:87]
	v_mfma_f32_16x16x32_bf16 v[80:83], v[186:189], v[214:217], v[80:83]
	v_mfma_f32_16x16x32_bf16 v[68:71], v[178:181], v[222:225], v[68:71]
	v_mfma_f32_16x16x32_bf16 v[64:67], v[186:189], v[222:225], v[64:67]
	v_mfma_f32_16x16x32_bf16 v[116:119], v[182:185], v[198:201], v[116:119]
	v_mfma_f32_16x16x32_bf16 v[112:115], v[190:193], v[198:201], v[112:115]
	v_mfma_f32_16x16x32_bf16 v[100:103], v[182:185], v[206:209], v[100:103]
	v_mfma_f32_16x16x32_bf16 v[96:99], v[190:193], v[206:209], v[96:99]
	v_mfma_f32_16x16x32_bf16 v[84:87], v[182:185], v[218:221], v[84:87]
	v_mfma_f32_16x16x32_bf16 v[80:83], v[190:193], v[218:221], v[80:83]
	v_mfma_f32_16x16x32_bf16 v[68:71], v[182:185], v[226:229], v[68:71]
	v_mfma_f32_16x16x32_bf16 v[64:67], v[190:193], v[226:229], v[64:67]
	s_barrier
	s_add_i32 s54, s69, s47
	v_lshl_add_u64 v[210:211], s[40:41], 0, v[138:139]
	s_mov_b32 m0, s54
	ds_read_b128 v[194:197], v173 offset:16384
	ds_read_b128 v[198:201], v173 offset:17408
	ds_read_b128 v[202:205], v173 offset:18432
	ds_read_b128 v[206:209], v173 offset:19456
	ds_read_b128 v[214:217], v173 offset:20480
	ds_read_b128 v[218:221], v173 offset:21504
	ds_read_b128 v[222:225], v173 offset:22528
	ds_read_b128 v[226:229], v173 offset:23552
	global_load_lds_dwordx4 v[210:211], off
	s_add_i32 m0, s54, 0x2000
	s_add_u32 s54, s40, 0x80000
	v_lshl_add_u64 v[230:231], s[40:41], 0, v[142:143]
	s_addc_u32 s55, s41, 0
	s_add_i32 s60, s70, s47
	global_load_lds_dwordx4 v[230:231], off
	v_lshl_add_u64 v[232:233], s[54:55], 0, v[138:139]
	s_mov_b32 m0, s60
	v_lshl_add_u64 v[234:235], s[42:43], 0, v[140:141]
	global_load_lds_dwordx4 v[232:233], off
	v_lshl_add_u64 v[232:233], s[54:55], 0, v[142:143]
	s_add_i32 m0, s60, 0x2000
	s_nop 0
	global_load_lds_dwordx4 v[232:233], off
	v_lshl_add_u64 v[232:233], s[42:43], 0, v[136:137]
	s_mov_b32 m0, s37
	s_nop 0
	global_load_lds_dwordx4 v[232:233], off
	s_mov_b32 m0, s48
	s_nop 0
	global_load_lds_dwordx4 v[234:235], off
	s_waitcnt vmcnt(8)
	s_waitcnt lgkmcnt(0)
	s_barrier
	s_waitcnt lgkmcnt(0)
	v_mfma_f32_16x16x32_bf16 v[60:63], v[128:131], v[194:197], v[60:63]
	v_mfma_f32_16x16x32_bf16 v[56:59], v[168:171], v[194:197], v[56:59]
	v_mfma_f32_16x16x32_bf16 v[44:47], v[128:131], v[202:205], v[44:47]
	v_mfma_f32_16x16x32_bf16 v[40:43], v[168:171], v[202:205], v[40:43]
	v_mfma_f32_16x16x32_bf16 v[28:31], v[128:131], v[214:217], v[28:31]
	v_mfma_f32_16x16x32_bf16 v[24:27], v[168:171], v[214:217], v[24:27]
	v_mfma_f32_16x16x32_bf16 v[12:15], v[128:131], v[222:225], v[12:15]
	v_mfma_f32_16x16x32_bf16 v[8:11], v[168:171], v[222:225], v[8:11]
	v_mfma_f32_16x16x32_bf16 v[60:63], v[132:135], v[198:201], v[60:63]
	v_mfma_f32_16x16x32_bf16 v[56:59], v[174:177], v[198:201], v[56:59]
	v_mfma_f32_16x16x32_bf16 v[44:47], v[132:135], v[206:209], v[44:47]
	v_mfma_f32_16x16x32_bf16 v[40:43], v[174:177], v[206:209], v[40:43]
	v_mfma_f32_16x16x32_bf16 v[28:31], v[132:135], v[218:221], v[28:31]
	v_mfma_f32_16x16x32_bf16 v[24:27], v[174:177], v[218:221], v[24:27]
	v_mfma_f32_16x16x32_bf16 v[12:15], v[132:135], v[226:229], v[12:15]
	v_mfma_f32_16x16x32_bf16 v[8:11], v[174:177], v[226:229], v[8:11]
	v_mfma_f32_16x16x32_bf16 v[52:55], v[178:181], v[194:197], v[52:55]
	v_mfma_f32_16x16x32_bf16 v[48:51], v[186:189], v[194:197], v[48:51]
	v_mfma_f32_16x16x32_bf16 v[36:39], v[178:181], v[202:205], v[36:39]
	v_mfma_f32_16x16x32_bf16 v[32:35], v[186:189], v[202:205], v[32:35]
	v_mfma_f32_16x16x32_bf16 v[20:23], v[178:181], v[214:217], v[20:23]
	v_mfma_f32_16x16x32_bf16 v[16:19], v[186:189], v[214:217], v[16:19]
	v_mfma_f32_16x16x32_bf16 v[4:7], v[178:181], v[222:225], v[4:7]
	v_mfma_f32_16x16x32_bf16 v[0:3], v[186:189], v[222:225], v[0:3]
	v_mfma_f32_16x16x32_bf16 v[52:55], v[182:185], v[198:201], v[52:55]
	v_mfma_f32_16x16x32_bf16 v[48:51], v[190:193], v[198:201], v[48:51]
	v_mfma_f32_16x16x32_bf16 v[36:39], v[182:185], v[206:209], v[36:39]
	v_mfma_f32_16x16x32_bf16 v[32:35], v[190:193], v[206:209], v[32:35]
	v_mfma_f32_16x16x32_bf16 v[20:23], v[182:185], v[218:221], v[20:23]
	v_mfma_f32_16x16x32_bf16 v[16:19], v[190:193], v[218:221], v[16:19]
	v_mfma_f32_16x16x32_bf16 v[4:7], v[182:185], v[226:229], v[4:7]
	v_mfma_f32_16x16x32_bf16 v[0:3], v[190:193], v[226:229], v[0:3]
	s_barrier
	s_add_i32 s54, 0, 0x18000
	v_add_u32_e32 v144, s54, v147
	s_add_i32 s55, 0, 0x1c000
	ds_read_b128 v[128:131], v144
	ds_read_b128 v[132:135], v144 offset:1024
	ds_read_b128 v[168:171], v144 offset:2048
	ds_read_b128 v[174:177], v144 offset:3072
	v_add_u32_e32 v144, s55, v147
	ds_read_b128 v[178:181], v144
	ds_read_b128 v[182:185], v144 offset:1024
	ds_read_b128 v[186:189], v144 offset:2048
	ds_read_b128 v[190:193], v144 offset:3072
	s_add_u32 s42, s42, 0x80000
	s_addc_u32 s43, s43, 0
	s_mov_b32 m0, s49
	v_lshl_add_u64 v[236:237], s[42:43], 0, v[136:137]
	ds_read_b128 v[194:197], v173 offset:32768
	ds_read_b128 v[198:201], v173 offset:33792
	ds_read_b128 v[202:205], v173 offset:34816
	ds_read_b128 v[206:209], v173 offset:35840
	ds_read_b128 v[214:217], v173 offset:36864
	ds_read_b128 v[218:221], v173 offset:37888
	ds_read_b128 v[222:225], v173 offset:38912
	ds_read_b128 v[226:229], v173 offset:39936
	global_load_lds_dwordx4 v[236:237], off
	v_lshl_add_u64 v[236:237], s[42:43], 0, v[140:141]
	s_mov_b32 m0, s52
	s_nop 0
	global_load_lds_dwordx4 v[236:237], off
	s_waitcnt vmcnt(8)
	s_waitcnt lgkmcnt(0)
	s_barrier
	s_waitcnt lgkmcnt(0)
	v_mfma_f32_16x16x32_bf16 v[124:127], v[128:131], v[194:197], v[124:127]
	v_mfma_f32_16x16x32_bf16 v[120:123], v[168:171], v[194:197], v[120:123]
	v_mfma_f32_16x16x32_bf16 v[108:111], v[128:131], v[202:205], v[108:111]
	v_mfma_f32_16x16x32_bf16 v[104:107], v[168:171], v[202:205], v[104:107]
	v_mfma_f32_16x16x32_bf16 v[92:95], v[128:131], v[214:217], v[92:95]
	v_mfma_f32_16x16x32_bf16 v[88:91], v[168:171], v[214:217], v[88:91]
	v_mfma_f32_16x16x32_bf16 v[76:79], v[128:131], v[222:225], v[76:79]
	v_mfma_f32_16x16x32_bf16 v[72:75], v[168:171], v[222:225], v[72:75]
	v_mfma_f32_16x16x32_bf16 v[124:127], v[132:135], v[198:201], v[124:127]
	v_mfma_f32_16x16x32_bf16 v[120:123], v[174:177], v[198:201], v[120:123]
	v_mfma_f32_16x16x32_bf16 v[108:111], v[132:135], v[206:209], v[108:111]
	v_mfma_f32_16x16x32_bf16 v[104:107], v[174:177], v[206:209], v[104:107]
	v_mfma_f32_16x16x32_bf16 v[92:95], v[132:135], v[218:221], v[92:95]
	v_mfma_f32_16x16x32_bf16 v[88:91], v[174:177], v[218:221], v[88:91]
	v_mfma_f32_16x16x32_bf16 v[76:79], v[132:135], v[226:229], v[76:79]
	v_mfma_f32_16x16x32_bf16 v[72:75], v[174:177], v[226:229], v[72:75]
	v_mfma_f32_16x16x32_bf16 v[116:119], v[178:181], v[194:197], v[116:119]
	v_mfma_f32_16x16x32_bf16 v[112:115], v[186:189], v[194:197], v[112:115]
	v_mfma_f32_16x16x32_bf16 v[100:103], v[178:181], v[202:205], v[100:103]
	v_mfma_f32_16x16x32_bf16 v[96:99], v[186:189], v[202:205], v[96:99]
	v_mfma_f32_16x16x32_bf16 v[84:87], v[178:181], v[214:217], v[84:87]
	v_mfma_f32_16x16x32_bf16 v[80:83], v[186:189], v[214:217], v[80:83]
	v_mfma_f32_16x16x32_bf16 v[68:71], v[178:181], v[222:225], v[68:71]
	v_mfma_f32_16x16x32_bf16 v[64:67], v[186:189], v[222:225], v[64:67]
	v_mfma_f32_16x16x32_bf16 v[116:119], v[182:185], v[198:201], v[116:119]
	v_mfma_f32_16x16x32_bf16 v[112:115], v[190:193], v[198:201], v[112:115]
	v_mfma_f32_16x16x32_bf16 v[100:103], v[182:185], v[206:209], v[100:103]
	v_mfma_f32_16x16x32_bf16 v[96:99], v[190:193], v[206:209], v[96:99]
	v_mfma_f32_16x16x32_bf16 v[84:87], v[182:185], v[218:221], v[84:87]
	v_mfma_f32_16x16x32_bf16 v[80:83], v[190:193], v[218:221], v[80:83]
	v_mfma_f32_16x16x32_bf16 v[68:71], v[182:185], v[226:229], v[68:71]
	v_mfma_f32_16x16x32_bf16 v[64:67], v[190:193], v[226:229], v[64:67]
	s_barrier
	s_add_i32 s42, s54, s47
	v_lshl_add_u64 v[210:211], v[210:211], 0, s[8:9]
	s_mov_b32 m0, s42
	ds_read_b128 v[194:197], v173 offset:49152
	ds_read_b128 v[198:201], v173 offset:50176
	ds_read_b128 v[202:205], v173 offset:51200
	ds_read_b128 v[206:209], v173 offset:52224
	ds_read_b128 v[214:217], v173 offset:53248
	ds_read_b128 v[218:221], v173 offset:54272
	ds_read_b128 v[222:225], v173 offset:55296
	ds_read_b128 v[226:229], v173 offset:56320
	global_load_lds_dwordx4 v[210:211], off
	s_add_i32 m0, s42, 0x2000
	s_add_u32 s40, s40, 0x80080
	v_lshl_add_u64 v[210:211], v[230:231], 0, s[8:9]
	s_addc_u32 s41, s41, 0
	s_add_i32 s42, s55, s47
	global_load_lds_dwordx4 v[210:211], off
	v_lshl_add_u64 v[210:211], s[40:41], 0, v[138:139]
	s_mov_b32 m0, s42
	s_nop 0
	global_load_lds_dwordx4 v[210:211], off
	v_lshl_add_u64 v[210:211], s[40:41], 0, v[142:143]
	s_add_i32 m0, s42, 0x2000
	s_nop 0
	global_load_lds_dwordx4 v[210:211], off
	v_lshl_add_u64 v[210:211], v[232:233], 0, s[8:9]
	s_mov_b32 m0, s53
	s_nop 0
	global_load_lds_dwordx4 v[210:211], off
	v_lshl_add_u64 v[210:211], v[234:235], 0, s[8:9]
	s_mov_b32 m0, s56
	s_nop 0
	global_load_lds_dwordx4 v[210:211], off
	s_waitcnt vmcnt(8)
	s_waitcnt lgkmcnt(0)
	s_barrier
	s_waitcnt lgkmcnt(0)
	v_mfma_f32_16x16x32_bf16 v[60:63], v[128:131], v[194:197], v[60:63]
	v_mfma_f32_16x16x32_bf16 v[56:59], v[168:171], v[194:197], v[56:59]
	v_mfma_f32_16x16x32_bf16 v[44:47], v[128:131], v[202:205], v[44:47]
	v_mfma_f32_16x16x32_bf16 v[40:43], v[168:171], v[202:205], v[40:43]
	v_mfma_f32_16x16x32_bf16 v[28:31], v[128:131], v[214:217], v[28:31]
	v_mfma_f32_16x16x32_bf16 v[24:27], v[168:171], v[214:217], v[24:27]
	v_mfma_f32_16x16x32_bf16 v[12:15], v[128:131], v[222:225], v[12:15]
	v_mfma_f32_16x16x32_bf16 v[8:11], v[168:171], v[222:225], v[8:11]
	v_mfma_f32_16x16x32_bf16 v[60:63], v[132:135], v[198:201], v[60:63]
	v_mfma_f32_16x16x32_bf16 v[56:59], v[174:177], v[198:201], v[56:59]
	v_mfma_f32_16x16x32_bf16 v[44:47], v[132:135], v[206:209], v[44:47]
	v_mfma_f32_16x16x32_bf16 v[40:43], v[174:177], v[206:209], v[40:43]
	v_mfma_f32_16x16x32_bf16 v[28:31], v[132:135], v[218:221], v[28:31]
	v_mfma_f32_16x16x32_bf16 v[24:27], v[174:177], v[218:221], v[24:27]
	v_mfma_f32_16x16x32_bf16 v[12:15], v[132:135], v[226:229], v[12:15]
	v_mfma_f32_16x16x32_bf16 v[8:11], v[174:177], v[226:229], v[8:11]
	v_mfma_f32_16x16x32_bf16 v[52:55], v[178:181], v[194:197], v[52:55]
	v_mfma_f32_16x16x32_bf16 v[48:51], v[186:189], v[194:197], v[48:51]
	v_mfma_f32_16x16x32_bf16 v[36:39], v[178:181], v[202:205], v[36:39]
	v_mfma_f32_16x16x32_bf16 v[32:35], v[186:189], v[202:205], v[32:35]
	v_mfma_f32_16x16x32_bf16 v[20:23], v[178:181], v[214:217], v[20:23]
	v_mfma_f32_16x16x32_bf16 v[16:19], v[186:189], v[214:217], v[16:19]
	v_mfma_f32_16x16x32_bf16 v[4:7], v[178:181], v[222:225], v[4:7]
	v_mfma_f32_16x16x32_bf16 v[0:3], v[186:189], v[222:225], v[0:3]
	v_mfma_f32_16x16x32_bf16 v[52:55], v[182:185], v[198:201], v[52:55]
	v_mfma_f32_16x16x32_bf16 v[48:51], v[190:193], v[198:201], v[48:51]
	v_mfma_f32_16x16x32_bf16 v[36:39], v[182:185], v[206:209], v[36:39]
	v_mfma_f32_16x16x32_bf16 v[32:35], v[190:193], v[206:209], v[32:35]
	v_mfma_f32_16x16x32_bf16 v[20:23], v[182:185], v[218:221], v[20:23]
	v_mfma_f32_16x16x32_bf16 v[16:19], v[190:193], v[218:221], v[16:19]
	v_mfma_f32_16x16x32_bf16 v[4:7], v[182:185], v[226:229], v[4:7]
	v_mfma_f32_16x16x32_bf16 v[0:3], v[190:193], v[226:229], v[0:3]
	s_barrier
	s_add_i32 s45, s45, 2
	s_add_u32 s38, s38, 0x100
	s_addc_u32 s39, s39, 0
	s_add_u32 s33, s33, 0x100
	s_addc_u32 s44, s44, 0
	s_cmp_gt_u32 s45, 29
	s_cbranch_scc0 .LBB0_1480
	s_and_b64 vcc, exec, s[10:11]
	s_cbranch_vccz .LBB0_1483
	s_barrier
